# read-once f32 weight loads of the conversion items marked nt (streaming), so they do not displace activations from L2/MALL
# speedup vs baseline: 1.0068x; 1.0068x over previous
.LBB0_608:
	s_lshl_b32 s11, s10, 2
	s_andn2_b32 s11, s11, 63
	s_addk_i32 s11, 0x4000
	v_add_u32_e32 v0, s11, v114
	s_lshl_b32 s12, s10, 6
	v_ashrrev_i32_e32 v1, 31, v0
	s_and_b32 s12, s12, 0x3c0
	v_lshlrev_b64 v[0:1], 10, v[0:1]
	v_or_b32_e32 v0, s12, v0
	v_or_b32_e32 v0, v0, v72
	v_readlane_b32 s12, v254, 2
	v_lshlrev_b64 v[0:1], 1, v[0:1]
	v_readlane_b32 s13, v254, 3
	v_lshl_add_u64 v[80:81], s[78:79], 0, v[0:1]
	s_andn2_b64 vcc, exec, s[4:5]
	v_lshl_add_u64 v[0:1], s[12:13], 0, v[0:1]
	global_load_dwordx4 v[4:7], v[80:81], off
	s_nop 0
	global_load_dwordx4 v[0:3], v[0:1], off nt
	s_cbranch_vccnz .LBB0_606
	s_and_b32 s11, s7, 0x3c0
	v_or_b32_e32 v14, s11, v73
	v_lshlrev_b32_e32 v15, 1, v14
	v_or_b32_e32 v8, 32, v15
	v_mad_i64_i32 v[82:83], s[12:13], s0, v8, v[76:77]
	v_or_b32_e32 v8, 0x60, v15
	s_and_b32 s11, s6, 0xffffffc0
	v_mad_i64_i32 v[84:85], s[12:13], s0, v8, v[76:77]
	v_add_u32_e32 v8, s11, v125
	v_ashrrev_i32_e32 v9, 31, v8
	v_lshlrev_b64 v[10:11], 1, v[8:9]
	v_lshl_add_u64 v[12:13], v[10:11], 0, 64
	v_mul_lo_u32 v13, s0, v13
	v_mul_lo_u32 v16, s1, v12
	v_mad_u64_u32 v[86:87], s[12:13], s0, v12, v[78:79]
	v_add3_u32 v87, v16, v87, v13
	v_lshl_add_u64 v[12:13], v[10:11], 0, s[42:43]
	v_mul_lo_u32 v13, s0, v13
	v_mul_lo_u32 v16, s1, v12
	v_mad_u64_u32 v[88:89], s[12:13], s0, v12, v[78:79]
	v_or_b32_e32 v12, 64, v15
	v_lshl_add_u64 v[10:11], v[10:11], 0, 32
	v_add3_u32 v89, v16, v89, v13
	v_mad_i64_i32 v[90:91], s[12:13], s0, v12, v[76:77]
	v_mad_u64_u32 v[92:93], s[12:13], s8, v14, v[76:77]
	v_mul_lo_u32 v11, s0, v11
	v_mul_lo_u32 v12, s1, v10
	v_mad_u64_u32 v[94:95], s[12:13], s0, v10, v[78:79]
	v_mul_lo_u32 v9, s8, v9
	v_mul_lo_u32 v10, s9, v8
	v_mad_u64_u32 v[96:97], s[12:13], s8, v8, v[78:79]
	v_mov_b32_e32 v16, 0
	v_mad_i32_i24 v93, s9, v14, v93
	v_add3_u32 v95, v12, v95, v11
	v_add3_u32 v97, v10, v97, v9
	s_mov_b32 s11, 0
	v_mov_b32_e32 v17, v16
	v_mov_b32_e32 v18, v16
	v_mov_b32_e32 v19, v16
	v_mov_b32_e32 v40, v16
	v_mov_b32_e32 v41, v16
	v_mov_b32_e32 v42, v16
	v_mov_b32_e32 v43, v16
	v_mov_b32_e32 v44, v16
	v_mov_b32_e32 v45, v16
	v_mov_b32_e32 v46, v16
	v_mov_b32_e32 v47, v16
	v_mov_b32_e32 v48, v16
	v_mov_b32_e32 v49, v16
	v_mov_b32_e32 v50, v16
	v_mov_b32_e32 v51, v16
	v_mov_b32_e32 v52, v16
	v_mov_b32_e32 v53, v16
	v_mov_b32_e32 v54, v16
	v_mov_b32_e32 v55, v16
	v_mov_b32_e32 v32, v16
	v_mov_b32_e32 v33, v16
	v_mov_b32_e32 v34, v16
	v_mov_b32_e32 v35, v16
	v_mov_b32_e32 v24, v16
	v_mov_b32_e32 v25, v16
	v_mov_b32_e32 v26, v16
	v_mov_b32_e32 v27, v16
	v_mov_b32_e32 v12, v16
	v_mov_b32_e32 v13, v16
	v_mov_b32_e32 v14, v16
	v_mov_b32_e32 v15, v16
	v_mov_b32_e32 v36, v16
	v_mov_b32_e32 v37, v16
	v_mov_b32_e32 v38, v16
	v_mov_b32_e32 v39, v16
	v_mov_b32_e32 v28, v16
	v_mov_b32_e32 v29, v16
	v_mov_b32_e32 v30, v16
	v_mov_b32_e32 v31, v16
	v_mov_b32_e32 v20, v16
	v_mov_b32_e32 v21, v16
	v_mov_b32_e32 v22, v16
	v_mov_b32_e32 v23, v16
	v_mov_b32_e32 v8, v16
	v_mov_b32_e32 v9, v16
	v_mov_b32_e32 v10, v16
	v_mov_b32_e32 v11, v16
	v_mov_b32_e32 v64, v16
	v_mov_b32_e32 v65, v16
	v_mov_b32_e32 v66, v16
	v_mov_b32_e32 v67, v16
	v_mov_b32_e32 v60, v16
	v_mov_b32_e32 v61, v16
	v_mov_b32_e32 v62, v16
	v_mov_b32_e32 v63, v16
	v_mov_b32_e32 v68, v16
	v_mov_b32_e32 v69, v16
	v_mov_b32_e32 v70, v16
	v_mov_b32_e32 v71, v16
	v_mov_b32_e32 v56, v16
	v_mov_b32_e32 v57, v16
	v_mov_b32_e32 v58, v16
	v_mov_b32_e32 v59, v16
	s_cmpk_lg_i32 s3, 0x100
	s_cbranch_scc1 .LBB0_610
	v_lshl_add_u64 v[112:113], v[92:93], 0, v[74:75]
	v_lshl_add_u64 v[110:111], v[82:83], 0, v[74:75]
	v_lshl_add_u64 v[106:107], v[90:91], 0, v[74:75]
	v_lshl_add_u64 v[104:105], v[84:85], 0, v[74:75]
	v_lshl_add_u64 v[108:109], v[96:97], 0, v[74:75]
	v_lshl_add_u64 v[100:101], v[94:95], 0, v[74:75]
	v_lshl_add_u64 v[102:103], v[86:87], 0, v[74:75]
	v_lshl_add_u64 v[98:99], v[88:89], 0, v[74:75]
	global_load_dwordx4 v[130:133], v[112:113], off
	global_load_dwordx4 v[134:137], v[110:111], off
	global_load_dwordx4 v[138:141], v[106:107], off
	global_load_dwordx4 v[142:145], v[104:105], off
	global_load_dwordx4 v[146:149], v[108:109], off
	global_load_dwordx4 v[150:153], v[100:101], off
	global_load_dwordx4 v[154:157], v[102:103], off
	global_load_dwordx4 v[158:161], v[98:99], off
	global_load_dwordx4 v[162:165], v[112:113], off offset:16
	global_load_dwordx4 v[166:169], v[110:111], off offset:16
	global_load_dwordx4 v[170:173], v[106:107], off offset:16
	global_load_dwordx4 v[174:177], v[104:105], off offset:16
	global_load_dwordx4 v[178:181], v[108:109], off offset:16
	global_load_dwordx4 v[182:185], v[100:101], off offset:16
	global_load_dwordx4 v[186:189], v[102:103], off offset:16
	global_load_dwordx4 v[198:201], v[98:99], off offset:16
	global_load_dwordx4 v[218:221], v[112:113], off offset:128
	global_load_dwordx4 v[222:225], v[110:111], off offset:128
	global_load_dwordx4 v[226:229], v[106:107], off offset:128
	global_load_dwordx4 v[230:233], v[104:105], off offset:128
	global_load_dwordx4 v[234:237], v[108:109], off offset:128
	global_load_dwordx4 v[238:241], v[100:101], off offset:128
	global_load_dwordx4 v[246:249], v[102:103], off offset:128
	s_waitcnt vmcnt(18)
	v_mfma_f32_16x16x32_bf16 v[16:19], v[130:133], v[146:149], v[16:19]
	s_waitcnt vmcnt(18)
	v_mfma_f32_16x16x32_bf16 v[40:43], v[134:137], v[146:149], v[40:43]
	s_waitcnt vmcnt(18)
	v_mfma_f32_16x16x32_bf16 v[44:47], v[138:141], v[146:149], v[44:47]
	s_waitcnt vmcnt(18)
	v_mfma_f32_16x16x32_bf16 v[48:51], v[142:145], v[146:149], v[48:51]
	global_load_dwordx4 v[146:149], v[98:99], off offset:128
	s_waitcnt vmcnt(18)
	v_mfma_f32_16x16x32_bf16 v[52:55], v[130:133], v[150:153], v[52:55]
	v_mfma_f32_16x16x32_bf16 v[32:35], v[134:137], v[150:153], v[32:35]
	v_mfma_f32_16x16x32_bf16 v[24:27], v[138:141], v[150:153], v[24:27]
	v_mfma_f32_16x16x32_bf16 v[12:15], v[142:145], v[150:153], v[12:15]
	global_load_dwordx4 v[150:153], v[112:113], off offset:144
	s_waitcnt vmcnt(18)
	v_mfma_f32_16x16x32_bf16 v[36:39], v[130:133], v[154:157], v[36:39]
	v_mfma_f32_16x16x32_bf16 v[28:31], v[134:137], v[154:157], v[28:31]
	v_mfma_f32_16x16x32_bf16 v[20:23], v[138:141], v[154:157], v[20:23]
	v_mfma_f32_16x16x32_bf16 v[8:11], v[142:145], v[154:157], v[8:11]
	global_load_dwordx4 v[154:157], v[110:111], off offset:144
	s_waitcnt vmcnt(18)
	v_mfma_f32_16x16x32_bf16 v[64:67], v[130:133], v[158:161], v[64:67]
	global_load_dwordx4 v[130:133], v[106:107], off offset:144
	v_mfma_f32_16x16x32_bf16 v[60:63], v[134:137], v[158:161], v[60:63]
	global_load_dwordx4 v[134:137], v[104:105], off offset:144
	v_mfma_f32_16x16x32_bf16 v[68:71], v[138:141], v[158:161], v[68:71]
	global_load_dwordx4 v[138:141], v[108:109], off offset:144
	v_mfma_f32_16x16x32_bf16 v[56:59], v[142:145], v[158:161], v[56:59]
	global_load_dwordx4 v[142:145], v[100:101], off offset:144
	global_load_dwordx4 v[158:161], v[102:103], off offset:144
	s_waitcnt vmcnt(18)
	v_mfma_f32_16x16x32_bf16 v[16:19], v[162:165], v[178:181], v[16:19]
	s_waitcnt vmcnt(18)
	v_mfma_f32_16x16x32_bf16 v[40:43], v[166:169], v[178:181], v[40:43]
	s_waitcnt vmcnt(18)
	v_mfma_f32_16x16x32_bf16 v[44:47], v[170:173], v[178:181], v[44:47]
	s_waitcnt vmcnt(18)
	v_mfma_f32_16x16x32_bf16 v[48:51], v[174:177], v[178:181], v[48:51]
	global_load_dwordx4 v[178:181], v[98:99], off offset:144
	s_waitcnt vmcnt(18)
	v_mfma_f32_16x16x32_bf16 v[52:55], v[162:165], v[182:185], v[52:55]
	v_mfma_f32_16x16x32_bf16 v[32:35], v[166:169], v[182:185], v[32:35]
	v_mfma_f32_16x16x32_bf16 v[24:27], v[170:173], v[182:185], v[24:27]
	v_mfma_f32_16x16x32_bf16 v[12:15], v[174:177], v[182:185], v[12:15]
	global_load_dwordx4 v[182:185], v[112:113], off offset:256
	s_waitcnt vmcnt(18)
	v_mfma_f32_16x16x32_bf16 v[36:39], v[162:165], v[186:189], v[36:39]
	v_mfma_f32_16x16x32_bf16 v[28:31], v[166:169], v[186:189], v[28:31]
	v_mfma_f32_16x16x32_bf16 v[20:23], v[170:173], v[186:189], v[20:23]
	v_mfma_f32_16x16x32_bf16 v[8:11], v[174:177], v[186:189], v[8:11]
	global_load_dwordx4 v[186:189], v[110:111], off offset:256
	s_waitcnt vmcnt(18)
	v_mfma_f32_16x16x32_bf16 v[64:67], v[162:165], v[198:201], v[64:67]
	global_load_dwordx4 v[162:165], v[106:107], off offset:256
	v_mfma_f32_16x16x32_bf16 v[60:63], v[166:169], v[198:201], v[60:63]
	global_load_dwordx4 v[166:169], v[104:105], off offset:256
	v_mfma_f32_16x16x32_bf16 v[68:71], v[170:173], v[198:201], v[68:71]
	global_load_dwordx4 v[170:173], v[108:109], off offset:256
	v_mfma_f32_16x16x32_bf16 v[56:59], v[174:177], v[198:201], v[56:59]
	global_load_dwordx4 v[174:177], v[100:101], off offset:256
	global_load_dwordx4 v[198:201], v[102:103], off offset:256
	s_waitcnt vmcnt(18)
	v_mfma_f32_16x16x32_bf16 v[16:19], v[218:221], v[234:237], v[16:19]
	s_waitcnt vmcnt(18)
	v_mfma_f32_16x16x32_bf16 v[40:43], v[222:225], v[234:237], v[40:43]
	s_waitcnt vmcnt(18)
	v_mfma_f32_16x16x32_bf16 v[44:47], v[226:229], v[234:237], v[44:47]
	s_waitcnt vmcnt(18)
	v_mfma_f32_16x16x32_bf16 v[48:51], v[230:233], v[234:237], v[48:51]
	global_load_dwordx4 v[234:237], v[98:99], off offset:256
	s_waitcnt vmcnt(18)
	v_mfma_f32_16x16x32_bf16 v[52:55], v[218:221], v[238:241], v[52:55]
	v_mfma_f32_16x16x32_bf16 v[32:35], v[222:225], v[238:241], v[32:35]
	v_mfma_f32_16x16x32_bf16 v[24:27], v[226:229], v[238:241], v[24:27]
	v_mfma_f32_16x16x32_bf16 v[12:15], v[230:233], v[238:241], v[12:15]
	global_load_dwordx4 v[238:241], v[112:113], off offset:272
	s_waitcnt vmcnt(18)
	v_mfma_f32_16x16x32_bf16 v[36:39], v[218:221], v[246:249], v[36:39]
	v_mfma_f32_16x16x32_bf16 v[28:31], v[222:225], v[246:249], v[28:31]
	v_mfma_f32_16x16x32_bf16 v[20:23], v[226:229], v[246:249], v[20:23]
	v_mfma_f32_16x16x32_bf16 v[8:11], v[230:233], v[246:249], v[8:11]
	global_load_dwordx4 v[246:249], v[110:111], off offset:272
	s_waitcnt vmcnt(18)
	v_mfma_f32_16x16x32_bf16 v[64:67], v[218:221], v[146:149], v[64:67]
	global_load_dwordx4 v[218:221], v[106:107], off offset:272
	v_mfma_f32_16x16x32_bf16 v[60:63], v[222:225], v[146:149], v[60:63]
	global_load_dwordx4 v[222:225], v[104:105], off offset:272
	v_mfma_f32_16x16x32_bf16 v[68:71], v[226:229], v[146:149], v[68:71]
	global_load_dwordx4 v[226:229], v[108:109], off offset:272
	v_mfma_f32_16x16x32_bf16 v[56:59], v[230:233], v[146:149], v[56:59]
	global_load_dwordx4 v[230:233], v[100:101], off offset:272
	global_load_dwordx4 v[146:149], v[102:103], off offset:272
	s_waitcnt vmcnt(18)
	v_mfma_f32_16x16x32_bf16 v[16:19], v[150:153], v[138:141], v[16:19]
	s_waitcnt vmcnt(18)
	v_mfma_f32_16x16x32_bf16 v[40:43], v[154:157], v[138:141], v[40:43]
	s_waitcnt vmcnt(18)
	v_mfma_f32_16x16x32_bf16 v[44:47], v[130:133], v[138:141], v[44:47]
	s_waitcnt vmcnt(18)
	v_mfma_f32_16x16x32_bf16 v[48:51], v[134:137], v[138:141], v[48:51]
	global_load_dwordx4 v[138:141], v[98:99], off offset:272
	s_waitcnt vmcnt(18)
	v_mfma_f32_16x16x32_bf16 v[52:55], v[150:153], v[142:145], v[52:55]
	v_mfma_f32_16x16x32_bf16 v[32:35], v[154:157], v[142:145], v[32:35]
	v_mfma_f32_16x16x32_bf16 v[24:27], v[130:133], v[142:145], v[24:27]
	v_mfma_f32_16x16x32_bf16 v[12:15], v[134:137], v[142:145], v[12:15]
	global_load_dwordx4 v[142:145], v[112:113], off offset:384
	s_waitcnt vmcnt(18)
	v_mfma_f32_16x16x32_bf16 v[36:39], v[150:153], v[158:161], v[36:39]
	v_mfma_f32_16x16x32_bf16 v[28:31], v[154:157], v[158:161], v[28:31]
	v_mfma_f32_16x16x32_bf16 v[20:23], v[130:133], v[158:161], v[20:23]
	v_mfma_f32_16x16x32_bf16 v[8:11], v[134:137], v[158:161], v[8:11]
	global_load_dwordx4 v[158:161], v[110:111], off offset:384
	s_waitcnt vmcnt(18)
	v_mfma_f32_16x16x32_bf16 v[64:67], v[150:153], v[178:181], v[64:67]
	global_load_dwordx4 v[150:153], v[106:107], off offset:384
	v_mfma_f32_16x16x32_bf16 v[60:63], v[154:157], v[178:181], v[60:63]
	global_load_dwordx4 v[154:157], v[104:105], off offset:384
	v_mfma_f32_16x16x32_bf16 v[68:71], v[130:133], v[178:181], v[68:71]
	global_load_dwordx4 v[130:133], v[108:109], off offset:384
	v_mfma_f32_16x16x32_bf16 v[56:59], v[134:137], v[178:181], v[56:59]
	global_load_dwordx4 v[134:137], v[100:101], off offset:384
	global_load_dwordx4 v[178:181], v[102:103], off offset:384
	s_waitcnt vmcnt(18)
	v_mfma_f32_16x16x32_bf16 v[16:19], v[182:185], v[170:173], v[16:19]
	s_waitcnt vmcnt(18)
	v_mfma_f32_16x16x32_bf16 v[40:43], v[186:189], v[170:173], v[40:43]
	s_waitcnt vmcnt(18)
	v_mfma_f32_16x16x32_bf16 v[44:47], v[162:165], v[170:173], v[44:47]
	s_waitcnt vmcnt(18)
	v_mfma_f32_16x16x32_bf16 v[48:51], v[166:169], v[170:173], v[48:51]
	global_load_dwordx4 v[170:173], v[98:99], off offset:384
	s_waitcnt vmcnt(18)
	v_mfma_f32_16x16x32_bf16 v[52:55], v[182:185], v[174:177], v[52:55]
	v_mfma_f32_16x16x32_bf16 v[32:35], v[186:189], v[174:177], v[32:35]
	v_mfma_f32_16x16x32_bf16 v[24:27], v[162:165], v[174:177], v[24:27]
	v_mfma_f32_16x16x32_bf16 v[12:15], v[166:169], v[174:177], v[12:15]
	global_load_dwordx4 v[174:177], v[112:113], off offset:400
	s_waitcnt vmcnt(18)
	v_mfma_f32_16x16x32_bf16 v[36:39], v[182:185], v[198:201], v[36:39]
	v_mfma_f32_16x16x32_bf16 v[28:31], v[186:189], v[198:201], v[28:31]
	v_mfma_f32_16x16x32_bf16 v[20:23], v[162:165], v[198:201], v[20:23]
	v_mfma_f32_16x16x32_bf16 v[8:11], v[166:169], v[198:201], v[8:11]
	global_load_dwordx4 v[198:201], v[110:111], off offset:400
	s_waitcnt vmcnt(18)
	v_mfma_f32_16x16x32_bf16 v[64:67], v[182:185], v[234:237], v[64:67]
	global_load_dwordx4 v[182:185], v[106:107], off offset:400
	v_mfma_f32_16x16x32_bf16 v[60:63], v[186:189], v[234:237], v[60:63]
	global_load_dwordx4 v[186:189], v[104:105], off offset:400
	v_mfma_f32_16x16x32_bf16 v[68:71], v[162:165], v[234:237], v[68:71]
	global_load_dwordx4 v[162:165], v[108:109], off offset:400
	v_mfma_f32_16x16x32_bf16 v[56:59], v[166:169], v[234:237], v[56:59]
	global_load_dwordx4 v[166:169], v[100:101], off offset:400
	global_load_dwordx4 v[234:237], v[102:103], off offset:400
	s_waitcnt vmcnt(18)
	v_mfma_f32_16x16x32_bf16 v[16:19], v[238:241], v[226:229], v[16:19]
	s_waitcnt vmcnt(18)
	v_mfma_f32_16x16x32_bf16 v[40:43], v[246:249], v[226:229], v[40:43]
	s_waitcnt vmcnt(18)
	v_mfma_f32_16x16x32_bf16 v[44:47], v[218:221], v[226:229], v[44:47]
	s_waitcnt vmcnt(18)
	v_mfma_f32_16x16x32_bf16 v[48:51], v[222:225], v[226:229], v[48:51]
	global_load_dwordx4 v[226:229], v[98:99], off offset:400
	s_waitcnt vmcnt(18)
	v_mfma_f32_16x16x32_bf16 v[52:55], v[238:241], v[230:233], v[52:55]
	v_mfma_f32_16x16x32_bf16 v[32:35], v[246:249], v[230:233], v[32:35]
	v_mfma_f32_16x16x32_bf16 v[24:27], v[218:221], v[230:233], v[24:27]
	v_mfma_f32_16x16x32_bf16 v[12:15], v[222:225], v[230:233], v[12:15]
	s_waitcnt vmcnt(17)
	v_mfma_f32_16x16x32_bf16 v[36:39], v[238:241], v[146:149], v[36:39]
	v_mfma_f32_16x16x32_bf16 v[28:31], v[246:249], v[146:149], v[28:31]
	v_mfma_f32_16x16x32_bf16 v[20:23], v[218:221], v[146:149], v[20:23]
	v_mfma_f32_16x16x32_bf16 v[8:11], v[222:225], v[146:149], v[8:11]
	s_waitcnt vmcnt(16)
	v_mfma_f32_16x16x32_bf16 v[64:67], v[238:241], v[138:141], v[64:67]
	v_mfma_f32_16x16x32_bf16 v[60:63], v[246:249], v[138:141], v[60:63]
	v_mfma_f32_16x16x32_bf16 v[68:71], v[218:221], v[138:141], v[68:71]
	v_mfma_f32_16x16x32_bf16 v[56:59], v[222:225], v[138:141], v[56:59]
	s_waitcnt vmcnt(11)
	v_mfma_f32_16x16x32_bf16 v[16:19], v[142:145], v[130:133], v[16:19]
	s_waitcnt vmcnt(11)
	v_mfma_f32_16x16x32_bf16 v[40:43], v[158:161], v[130:133], v[40:43]
	s_waitcnt vmcnt(11)
	v_mfma_f32_16x16x32_bf16 v[44:47], v[150:153], v[130:133], v[44:47]
	s_waitcnt vmcnt(11)
	v_mfma_f32_16x16x32_bf16 v[48:51], v[154:157], v[130:133], v[48:51]
	s_waitcnt vmcnt(10)
	v_mfma_f32_16x16x32_bf16 v[52:55], v[142:145], v[134:137], v[52:55]
	v_mfma_f32_16x16x32_bf16 v[32:35], v[158:161], v[134:137], v[32:35]
	v_mfma_f32_16x16x32_bf16 v[24:27], v[150:153], v[134:137], v[24:27]
	v_mfma_f32_16x16x32_bf16 v[12:15], v[154:157], v[134:137], v[12:15]
	s_waitcnt vmcnt(9)
	v_mfma_f32_16x16x32_bf16 v[36:39], v[142:145], v[178:181], v[36:39]
	v_mfma_f32_16x16x32_bf16 v[28:31], v[158:161], v[178:181], v[28:31]
	v_mfma_f32_16x16x32_bf16 v[20:23], v[150:153], v[178:181], v[20:23]
	v_mfma_f32_16x16x32_bf16 v[8:11], v[154:157], v[178:181], v[8:11]
	s_waitcnt vmcnt(8)
	v_mfma_f32_16x16x32_bf16 v[64:67], v[142:145], v[170:173], v[64:67]
	v_mfma_f32_16x16x32_bf16 v[60:63], v[158:161], v[170:173], v[60:63]
	v_mfma_f32_16x16x32_bf16 v[68:71], v[150:153], v[170:173], v[68:71]
	v_mfma_f32_16x16x32_bf16 v[56:59], v[154:157], v[170:173], v[56:59]
	s_waitcnt vmcnt(3)
	v_mfma_f32_16x16x32_bf16 v[16:19], v[174:177], v[162:165], v[16:19]
	s_waitcnt vmcnt(3)
	v_mfma_f32_16x16x32_bf16 v[40:43], v[198:201], v[162:165], v[40:43]
	s_waitcnt vmcnt(3)
	v_mfma_f32_16x16x32_bf16 v[44:47], v[182:185], v[162:165], v[44:47]
	s_waitcnt vmcnt(3)
	v_mfma_f32_16x16x32_bf16 v[48:51], v[186:189], v[162:165], v[48:51]
	s_waitcnt vmcnt(2)
	v_mfma_f32_16x16x32_bf16 v[52:55], v[174:177], v[166:169], v[52:55]
	v_mfma_f32_16x16x32_bf16 v[32:35], v[198:201], v[166:169], v[32:35]
	v_mfma_f32_16x16x32_bf16 v[24:27], v[182:185], v[166:169], v[24:27]
	v_mfma_f32_16x16x32_bf16 v[12:15], v[186:189], v[166:169], v[12:15]
	s_waitcnt vmcnt(1)
	v_mfma_f32_16x16x32_bf16 v[36:39], v[174:177], v[234:237], v[36:39]
	v_mfma_f32_16x16x32_bf16 v[28:31], v[198:201], v[234:237], v[28:31]
	v_mfma_f32_16x16x32_bf16 v[20:23], v[182:185], v[234:237], v[20:23]
	v_mfma_f32_16x16x32_bf16 v[8:11], v[186:189], v[234:237], v[8:11]
	s_waitcnt vmcnt(0)
	v_mfma_f32_16x16x32_bf16 v[64:67], v[174:177], v[226:229], v[64:67]
	v_mfma_f32_16x16x32_bf16 v[60:63], v[198:201], v[226:229], v[60:63]
	v_mfma_f32_16x16x32_bf16 v[68:71], v[182:185], v[226:229], v[68:71]
	v_mfma_f32_16x16x32_bf16 v[56:59], v[186:189], v[226:229], v[56:59]
	s_branch .LBB0_607

.LBB0_795:
	s_cmpk_gt_i32 s29, 0xcff
	s_mov_b64 s[0:1], -1
	s_cbranch_scc0 .LBB0_853
	s_cmpk_gt_u32 s29, 0xeff
	s_cbranch_scc0 .LBB0_850
	s_cmpk_gt_u32 s29, 0x10ff
	s_cbranch_scc0 .LBB0_847
	s_cmpk_gt_u32 s29, 0x12ff
	s_cbranch_scc0 .LBB0_844
	s_cmpk_gt_u32 s29, 0x137f
	s_cbranch_scc0 .LBB0_825
	s_cmpk_gt_u32 s29, 0x13ff
	s_cbranch_scc0 .LBB0_822
	v_lshlrev_b32_e32 v0, 2, v12
	v_ashrrev_i32_e32 v15, 3, v12
	v_and_b32_e32 v0, 28, v0
	s_cmpk_gt_u32 s29, 0x1bff
	v_lshl_add_u32 v4, v0, 2, s33
	v_add_u32_e32 v14, 8, v15
	v_add_u32_e32 v13, 16, v15
	v_add_u32_e32 v5, 24, v15
	v_lshlrev_b32_e32 v16, 2, v15
	v_lshlrev_b32_e32 v194, 2, v0
	s_cbranch_scc0 .LBB0_803
	s_and_b32 s0, s55, 0x3e0
	s_and_b32 s1, s25, 0x1ffc0
	s_lshl_b32 s3, s0, 2
	v_readlane_b32 s14, v255, 51
	s_add_u32 s14, s14, s3
	v_readlane_b32 s3, v255, 52
	v_add_u32_e32 v8, s1, v15
	s_addc_u32 s15, s3, 0
	v_ashrrev_i32_e32 v9, 31, v8
	v_lshl_add_u64 v[6:7], s[14:15], 0, v[194:195]
	v_lshlrev_b64 v[0:1], 12, v[8:9]
	v_lshl_add_u64 v[0:1], v[6:7], 0, v[0:1]
	global_load_dwordx4 v[0:3], v[0:1], off nt
	v_mad_u64_u32 v[10:11], s[14:15], v15, s49, v[4:5]
	v_add_u32_e32 v9, 0x420, v10
	v_add_u32_e32 v30, s0, v15
	v_ashrrev_i32_e32 v31, 31, v30
	v_lshlrev_b64 v[30:31], 13, v[30:31]
	s_waitcnt vmcnt(0)
	ds_write2_b32 v10, v0, v1 offset1:1
	ds_write2_b32 v10, v2, v3 offset0:2 offset1:3
	v_add_u32_e32 v0, s1, v14
	v_ashrrev_i32_e32 v1, 31, v0
	v_lshlrev_b64 v[0:1], 12, v[0:1]
	v_lshl_add_u64 v[0:1], v[6:7], 0, v[0:1]
	global_load_dwordx4 v[0:3], v[0:1], off nt
	s_waitcnt vmcnt(0)
	ds_write2_b32 v9, v0, v1 offset1:1
	v_add_u32_e32 v0, 0x428, v10
	ds_write2_b32 v0, v2, v3 offset1:1
	v_add_u32_e32 v0, s1, v13
	v_ashrrev_i32_e32 v1, 31, v0
	v_lshlrev_b64 v[0:1], 12, v[0:1]
	v_lshl_add_u64 v[0:1], v[6:7], 0, v[0:1]
	global_load_dwordx4 v[0:3], v[0:1], off nt
	v_add_u32_e32 v9, 0x840, v10
	s_waitcnt vmcnt(0)
	ds_write2_b32 v9, v0, v1 offset1:1
	v_add_u32_e32 v0, 0x848, v10
	ds_write2_b32 v0, v2, v3 offset1:1
	v_add_u32_e32 v0, s1, v5
	v_ashrrev_i32_e32 v1, 31, v0
	v_lshlrev_b64 v[0:1], 12, v[0:1]
	v_lshl_add_u64 v[0:1], v[6:7], 0, v[0:1]
	global_load_dwordx4 v[0:3], v[0:1], off nt
	v_add_u32_e32 v9, 0xc60, v10
	s_lshl_b32 s1, s1, 1
	s_add_u32 s14, s65, s1
	s_addc_u32 s15, s67, 0
	s_waitcnt vmcnt(0)
	ds_write2_b32 v9, v0, v1 offset1:1
	v_add_u32_e32 v0, 0xc68, v10
	ds_write2_b32 v0, v2, v3 offset1:1
	v_add_u32_e32 v0, 32, v8
	v_ashrrev_i32_e32 v1, 31, v0
	v_lshlrev_b64 v[0:1], 12, v[0:1]
	v_lshl_add_u64 v[0:1], v[6:7], 0, v[0:1]
	global_load_dwordx4 v[0:3], v[0:1], off nt
	v_add_u32_e32 v9, 0x1080, v10
	s_waitcnt vmcnt(0)
	ds_write2_b32 v9, v0, v1 offset1:1
	v_add_u32_e32 v0, 0x1088, v10
	ds_write2_b32 v0, v2, v3 offset1:1
	v_add_u32_e32 v0, 40, v8
	v_ashrrev_i32_e32 v1, 31, v0
	v_lshlrev_b64 v[0:1], 12, v[0:1]
	v_lshl_add_u64 v[0:1], v[6:7], 0, v[0:1]
	global_load_dwordx4 v[0:3], v[0:1], off nt
	v_add_u32_e32 v9, 0x14a0, v10
	s_waitcnt vmcnt(0)
	ds_write2_b32 v9, v0, v1 offset1:1
	v_add_u32_e32 v0, 0x14a8, v10
	ds_write2_b32 v0, v2, v3 offset1:1
	v_add_u32_e32 v0, 48, v8
	v_ashrrev_i32_e32 v1, 31, v0
	v_lshlrev_b64 v[0:1], 12, v[0:1]
	v_lshl_add_u64 v[0:1], v[6:7], 0, v[0:1]
	global_load_dwordx4 v[0:3], v[0:1], off nt
	v_add_u32_e32 v9, 0x18c0, v10
	s_waitcnt vmcnt(0)
	ds_write2_b32 v9, v0, v1 offset1:1
	v_add_u32_e32 v0, 0x18c8, v10
	ds_write2_b32 v0, v2, v3 offset1:1
	v_add_u32_e32 v0, 56, v8
	v_ashrrev_i32_e32 v1, 31, v0
	v_lshlrev_b64 v[0:1], 12, v[0:1]
	v_lshl_add_u64 v[0:1], v[6:7], 0, v[0:1]
	global_load_dwordx4 v[0:3], v[0:1], off nt
	v_add_u32_e32 v6, 0x1ce0, v10
	s_waitcnt vmcnt(0)
	ds_write2_b32 v6, v0, v1 offset1:1
	v_add_u32_e32 v0, 0x1ce8, v10
	ds_write2_b32 v0, v2, v3 offset1:1
	v_lshlrev_b32_e32 v0, 3, v12
	v_and_b32_e32 v0, 56, v0
	v_mul_u32_u24_e32 v2, 0x84, v0
	s_waitcnt lgkmcnt(0)
	v_add3_u32 v17, s33, v2, v16
	ds_read2_b32 v[2:3], v17 offset0:33 offset1:41
	ds_read2_b32 v[10:11], v17 offset1:8
	ds_read2_b32 v[18:19], v17 offset0:66 offset1:74
	ds_read2_b32 v[20:21], v17 offset0:99 offset1:107
	ds_read2_b32 v[22:23], v17 offset0:132 offset1:140
	ds_read2_b32 v[24:25], v17 offset0:165 offset1:173
	ds_read2_b32 v[26:27], v17 offset0:198 offset1:206
	ds_read2_b32 v[28:29], v17 offset0:231 offset1:239
	v_lshlrev_b32_e32 v0, 1, v0
	v_mov_b32_e32 v1, v195
	v_lshl_add_u64 v[0:1], s[14:15], 0, v[0:1]
	s_waitcnt lgkmcnt(6)
	v_cvt_pk_bf16_f32 v6, v10, v2
	s_waitcnt lgkmcnt(4)
	v_cvt_pk_bf16_f32 v7, v18, v20
	s_waitcnt lgkmcnt(2)
	v_cvt_pk_bf16_f32 v8, v22, v24
	s_waitcnt lgkmcnt(0)
	v_cvt_pk_bf16_f32 v9, v26, v28
	v_lshl_add_u64 v[30:31], v[0:1], 0, v[30:31]
	v_add_u32_e32 v2, s0, v14
	global_store_dwordx4 v[30:31], v[6:9], off
	v_add_u32_e32 v30, s0, v13
	v_ashrrev_i32_e32 v31, 31, v30
	v_cvt_pk_bf16_f32 v6, v11, v3
	v_ashrrev_i32_e32 v3, 31, v2
	v_lshlrev_b64 v[2:3], 13, v[2:3]
	v_cvt_pk_bf16_f32 v7, v19, v21
	v_cvt_pk_bf16_f32 v8, v23, v25
	v_cvt_pk_bf16_f32 v9, v27, v29
	v_lshl_add_u64 v[2:3], v[0:1], 0, v[2:3]
	global_store_dwordx4 v[2:3], v[6:9], off
	ds_read2_b32 v[2:3], v17 offset0:49 offset1:57
	ds_read2_b32 v[10:11], v17 offset0:16 offset1:24
	ds_read2_b32 v[18:19], v17 offset0:82 offset1:90
	ds_read2_b32 v[20:21], v17 offset0:115 offset1:123
	ds_read2_b32 v[22:23], v17 offset0:148 offset1:156
	ds_read2_b32 v[24:25], v17 offset0:181 offset1:189
	ds_read2_b32 v[26:27], v17 offset0:214 offset1:222
	ds_read2_b32 v[28:29], v17 offset0:247 offset1:255
	v_lshlrev_b64 v[30:31], 13, v[30:31]
	s_waitcnt lgkmcnt(6)
	v_cvt_pk_bf16_f32 v6, v10, v2
	s_waitcnt lgkmcnt(4)
	v_cvt_pk_bf16_f32 v7, v18, v20
	s_waitcnt lgkmcnt(2)
	v_cvt_pk_bf16_f32 v8, v22, v24
	s_waitcnt lgkmcnt(0)
	v_cvt_pk_bf16_f32 v9, v26, v28
	v_lshl_add_u64 v[30:31], v[0:1], 0, v[30:31]
	v_add_u32_e32 v2, s0, v5
	global_store_dwordx4 v[30:31], v[6:9], off
	s_mov_b64 s[0:1], 0
	s_nop 0
	v_cvt_pk_bf16_f32 v6, v11, v3
	v_ashrrev_i32_e32 v3, 31, v2
	v_lshlrev_b64 v[2:3], 13, v[2:3]
	v_cvt_pk_bf16_f32 v7, v19, v21
	v_cvt_pk_bf16_f32 v8, v23, v25
	v_cvt_pk_bf16_f32 v9, v27, v29
	v_lshl_add_u64 v[0:1], v[0:1], 0, v[2:3]
	global_store_dwordx4 v[0:1], v[6:9], off
	s_waitcnt lgkmcnt(0)
.LBB0_803:
	s_andn2_b64 vcc, exec, s[0:1]
	s_cbranch_vccnz .LBB0_821
	s_add_i32 s0, s29, 0xec00
	s_lshr_b32 s0, s0, 1
	s_and_b32 s3, s55, 0xfe0
	s_and_b32 s14, s0, 0x7fc0
	s_lshl_b32 s0, s3, 2
	v_readlane_b32 s1, v255, 53
	s_add_u32 s0, s1, s0
	v_readlane_b32 s1, v255, 54
	v_add_u32_e32 v10, s14, v15
	s_addc_u32 s1, s1, 0
	v_ashrrev_i32_e32 v11, 31, v10
	v_lshl_add_u64 v[8:9], s[0:1], 0, v[194:195]
	v_lshlrev_b64 v[0:1], 14, v[10:11]
	v_lshl_add_u64 v[0:1], v[8:9], 0, v[0:1]
	global_load_dwordx4 v[0:3], v[0:1], off nt
	v_readlane_b32 s42, v254, 37
	v_readlane_b32 s43, v254, 38
	s_andn2_b64 vcc, exec, s[42:43]
	s_nop 0
	v_cndmask_b32_e64 v6, 0, 1, s[42:43]
	v_cmp_ne_u32_e64 s[0:1], 1, v6
	v_lshl_add_u64 v[6:7], v[10:11], 2, s[4:5]
	s_cbranch_vccnz .LBB0_806
	global_load_dword v18, v[6:7], off
	s_waitcnt vmcnt(0)
	v_pk_mul_f32 v[2:3], v[2:3], v[18:19] op_sel_hi:[1,0]
	v_pk_mul_f32 v[0:1], v[0:1], v[18:19] op_sel_hi:[1,0]
.LBB0_806:
	v_mul_lo_u32 v11, v15, s49
	v_add_u32_e32 v4, v4, v11
	s_waitcnt vmcnt(0)
	ds_write2_b32 v4, v0, v1 offset1:1
	ds_write2_b32 v4, v2, v3 offset0:2 offset1:3
	v_add_u32_e32 v0, s14, v14
	v_ashrrev_i32_e32 v1, 31, v0
	v_lshlrev_b64 v[0:1], 14, v[0:1]
	v_lshl_add_u64 v[0:1], v[8:9], 0, v[0:1]
	global_load_dwordx4 v[0:3], v[0:1], off nt
	s_and_b64 vcc, exec, s[0:1]
	s_cbranch_vccnz .LBB0_808
	global_load_dword v18, v[6:7], off offset:32
	s_waitcnt vmcnt(0)
	v_pk_mul_f32 v[2:3], v[2:3], v[18:19] op_sel_hi:[1,0]
	v_pk_mul_f32 v[0:1], v[0:1], v[18:19] op_sel_hi:[1,0]
.LBB0_808:
	v_add_u32_e32 v11, 0x420, v4
	s_waitcnt vmcnt(0)
	ds_write2_b32 v11, v0, v1 offset1:1
	v_add_u32_e32 v0, 0x428, v4
	ds_write2_b32 v0, v2, v3 offset1:1
	v_add_u32_e32 v0, s14, v13
	v_ashrrev_i32_e32 v1, 31, v0
	v_lshlrev_b64 v[0:1], 14, v[0:1]
	v_lshl_add_u64 v[0:1], v[8:9], 0, v[0:1]
	global_load_dwordx4 v[0:3], v[0:1], off nt
	s_and_b64 vcc, exec, s[0:1]
	s_cbranch_vccnz .LBB0_810
	global_load_dword v18, v[6:7], off offset:64
	s_waitcnt vmcnt(0)
	v_pk_mul_f32 v[2:3], v[2:3], v[18:19] op_sel_hi:[1,0]
	v_pk_mul_f32 v[0:1], v[0:1], v[18:19] op_sel_hi:[1,0]
.LBB0_810:
	v_add_u32_e32 v11, 0x840, v4
	s_waitcnt vmcnt(0)
	ds_write2_b32 v11, v0, v1 offset1:1
	v_add_u32_e32 v0, 0x848, v4
	ds_write2_b32 v0, v2, v3 offset1:1
	v_add_u32_e32 v0, s14, v5
	v_ashrrev_i32_e32 v1, 31, v0
	v_lshlrev_b64 v[0:1], 14, v[0:1]
	v_lshl_add_u64 v[0:1], v[8:9], 0, v[0:1]
	global_load_dwordx4 v[0:3], v[0:1], off nt
	s_and_b64 vcc, exec, s[0:1]
	s_cbranch_vccnz .LBB0_812
	global_load_dword v18, v[6:7], off offset:96
	s_waitcnt vmcnt(0)
	v_pk_mul_f32 v[2:3], v[2:3], v[18:19] op_sel_hi:[1,0]
	v_pk_mul_f32 v[0:1], v[0:1], v[18:19] op_sel_hi:[1,0]
.LBB0_812:
	v_add_u32_e32 v11, 0xc60, v4
	s_waitcnt vmcnt(0)
	ds_write2_b32 v11, v0, v1 offset1:1
	v_add_u32_e32 v0, 0xc68, v4
	ds_write2_b32 v0, v2, v3 offset1:1
	v_add_u32_e32 v0, 32, v10
	v_ashrrev_i32_e32 v1, 31, v0
	v_lshlrev_b64 v[0:1], 14, v[0:1]
	v_lshl_add_u64 v[0:1], v[8:9], 0, v[0:1]
	global_load_dwordx4 v[0:3], v[0:1], off nt
	s_and_b64 vcc, exec, s[0:1]
	s_cbranch_vccnz .LBB0_814
	global_load_dword v18, v[6:7], off offset:128
	s_waitcnt vmcnt(0)
	v_pk_mul_f32 v[2:3], v[2:3], v[18:19] op_sel_hi:[1,0]
	v_pk_mul_f32 v[0:1], v[0:1], v[18:19] op_sel_hi:[1,0]
.LBB0_814:
	v_add_u32_e32 v11, 0x1080, v4
	s_waitcnt vmcnt(0)
	ds_write2_b32 v11, v0, v1 offset1:1
	v_add_u32_e32 v0, 0x1088, v4
	ds_write2_b32 v0, v2, v3 offset1:1
	v_add_u32_e32 v0, 40, v10
	v_ashrrev_i32_e32 v1, 31, v0
	v_lshlrev_b64 v[0:1], 14, v[0:1]
	v_lshl_add_u64 v[0:1], v[8:9], 0, v[0:1]
	global_load_dwordx4 v[0:3], v[0:1], off nt
	s_and_b64 vcc, exec, s[0:1]
	s_cbranch_vccnz .LBB0_816
	global_load_dword v18, v[6:7], off offset:160
	s_waitcnt vmcnt(0)
	v_pk_mul_f32 v[2:3], v[2:3], v[18:19] op_sel_hi:[1,0]
	v_pk_mul_f32 v[0:1], v[0:1], v[18:19] op_sel_hi:[1,0]
.LBB0_816:
	v_add_u32_e32 v11, 0x14a0, v4
	s_waitcnt vmcnt(0)
	ds_write2_b32 v11, v0, v1 offset1:1
	v_add_u32_e32 v0, 0x14a8, v4
	ds_write2_b32 v0, v2, v3 offset1:1
	v_add_u32_e32 v0, 48, v10
	v_ashrrev_i32_e32 v1, 31, v0
	v_lshlrev_b64 v[0:1], 14, v[0:1]
	v_lshl_add_u64 v[0:1], v[8:9], 0, v[0:1]
	global_load_dwordx4 v[0:3], v[0:1], off nt
	s_and_b64 vcc, exec, s[0:1]
	s_cbranch_vccnz .LBB0_818
	global_load_dword v18, v[6:7], off offset:192
	s_waitcnt vmcnt(0)
	v_pk_mul_f32 v[2:3], v[2:3], v[18:19] op_sel_hi:[1,0]
	v_pk_mul_f32 v[0:1], v[0:1], v[18:19] op_sel_hi:[1,0]
.LBB0_818:
	v_add_u32_e32 v11, 0x18c0, v4
	s_waitcnt vmcnt(0)
	ds_write2_b32 v11, v0, v1 offset1:1
	v_add_u32_e32 v0, 0x18c8, v4
	ds_write2_b32 v0, v2, v3 offset1:1
	v_add_u32_e32 v0, 56, v10
	v_ashrrev_i32_e32 v1, 31, v0
	v_lshlrev_b64 v[0:1], 14, v[0:1]
	v_lshl_add_u64 v[0:1], v[8:9], 0, v[0:1]
	global_load_dwordx4 v[0:3], v[0:1], off nt
	s_and_b64 vcc, exec, s[0:1]
	s_cbranch_vccnz .LBB0_820
	global_load_dword v6, v[6:7], off offset:224
	s_waitcnt vmcnt(0)
	v_pk_mul_f32 v[2:3], v[2:3], v[6:7] op_sel_hi:[1,0]
	v_pk_mul_f32 v[0:1], v[0:1], v[6:7] op_sel_hi:[1,0]

.LBB0_822:
	s_andn2_b64 vcc, exec, s[0:1]
	s_cbranch_vccnz .LBB0_824
	s_add_i32 s0, s25, 0xfffe3800
	s_and_b32 s0, s0, 0x1c0
	s_xor_b32 s1, s0, 0x100
	s_and_b32 s0, s55, 0x3e0
	v_ashrrev_i32_e32 v13, 3, v12
	s_lshl_b32 s3, s0, 2
	v_readlane_b32 s14, v255, 55
	s_add_u32 s14, s14, s3
	v_readlane_b32 s3, v255, 56
	v_lshlrev_b32_e32 v0, 4, v12
	v_add_u32_e32 v6, s1, v13
	s_addc_u32 s15, s3, 0
	v_and_b32_e32 v194, 0x70, v0
	v_ashrrev_i32_e32 v7, 31, v6
	v_lshl_add_u64 v[4:5], s[14:15], 0, v[194:195]
	v_lshlrev_b64 v[0:1], 12, v[6:7]
	v_lshl_add_u64 v[0:1], v[4:5], 0, v[0:1]
	global_load_dwordx4 v[0:3], v[0:1], off nt
	v_mul_lo_u32 v7, v13, s49
	v_add3_u32 v7, s33, v194, v7
	v_add_u32_e32 v26, 8, v13
	v_add_u32_e32 v8, 0x420, v7
	v_add_u32_e32 v27, 16, v13
	v_add_u32_e32 v28, 24, v13
	v_add_u32_e32 v24, s0, v13
	v_ashrrev_i32_e32 v25, 31, v24
	v_lshlrev_b64 v[24:25], 9, v[24:25]
	s_waitcnt vmcnt(0)
	ds_write2_b32 v7, v0, v1 offset1:1
	ds_write2_b32 v7, v2, v3 offset0:2 offset1:3
	v_add_u32_e32 v0, s1, v26
	v_ashrrev_i32_e32 v1, 31, v0
	v_lshlrev_b64 v[0:1], 12, v[0:1]
	v_lshl_add_u64 v[0:1], v[4:5], 0, v[0:1]
	global_load_dwordx4 v[0:3], v[0:1], off nt
	s_waitcnt vmcnt(0)
	ds_write2_b32 v8, v0, v1 offset1:1
	v_add_u32_e32 v0, 0x428, v7
	ds_write2_b32 v0, v2, v3 offset1:1
	v_add_u32_e32 v0, s1, v27
	v_ashrrev_i32_e32 v1, 31, v0
	v_lshlrev_b64 v[0:1], 12, v[0:1]
	v_lshl_add_u64 v[0:1], v[4:5], 0, v[0:1]
	global_load_dwordx4 v[0:3], v[0:1], off nt
	v_add_u32_e32 v8, 0x840, v7
	s_waitcnt vmcnt(0)
	ds_write2_b32 v8, v0, v1 offset1:1
	v_add_u32_e32 v0, 0x848, v7
	ds_write2_b32 v0, v2, v3 offset1:1
	v_add_u32_e32 v0, s1, v28
	v_ashrrev_i32_e32 v1, 31, v0
	v_lshlrev_b64 v[0:1], 12, v[0:1]
	v_lshl_add_u64 v[0:1], v[4:5], 0, v[0:1]
	global_load_dwordx4 v[0:3], v[0:1], off nt
	v_add_u32_e32 v8, 0xc60, v7
	s_lshl_b32 s1, s1, 1
	s_add_u32 s14, s82, s1
	v_readlane_b32 s1, v255, 48
	s_addc_u32 s15, s1, 0
	s_waitcnt vmcnt(0)
	ds_write2_b32 v8, v0, v1 offset1:1
	v_add_u32_e32 v0, 0xc68, v7
	ds_write2_b32 v0, v2, v3 offset1:1
	v_add_u32_e32 v0, 32, v6
	v_ashrrev_i32_e32 v1, 31, v0
	v_lshlrev_b64 v[0:1], 12, v[0:1]
	v_lshl_add_u64 v[0:1], v[4:5], 0, v[0:1]
	global_load_dwordx4 v[0:3], v[0:1], off nt
	v_add_u32_e32 v8, 0x1080, v7
	s_waitcnt vmcnt(0)
	ds_write2_b32 v8, v0, v1 offset1:1
	v_add_u32_e32 v0, 0x1088, v7
	ds_write2_b32 v0, v2, v3 offset1:1
	v_add_u32_e32 v0, 40, v6
	v_ashrrev_i32_e32 v1, 31, v0
	v_lshlrev_b64 v[0:1], 12, v[0:1]
	v_lshl_add_u64 v[0:1], v[4:5], 0, v[0:1]
	global_load_dwordx4 v[0:3], v[0:1], off nt
	v_add_u32_e32 v8, 0x14a0, v7
	s_waitcnt vmcnt(0)
	ds_write2_b32 v8, v0, v1 offset1:1
	v_add_u32_e32 v0, 0x14a8, v7
	ds_write2_b32 v0, v2, v3 offset1:1
	v_add_u32_e32 v0, 48, v6
	v_ashrrev_i32_e32 v1, 31, v0
	v_lshlrev_b64 v[0:1], 12, v[0:1]
	v_lshl_add_u64 v[0:1], v[4:5], 0, v[0:1]
	global_load_dwordx4 v[0:3], v[0:1], off nt
	v_add_u32_e32 v8, 0x18c0, v7
	s_waitcnt vmcnt(0)
	ds_write2_b32 v8, v0, v1 offset1:1
	v_add_u32_e32 v0, 0x18c8, v7
	ds_write2_b32 v0, v2, v3 offset1:1
	v_add_u32_e32 v0, 56, v6
	v_ashrrev_i32_e32 v1, 31, v0
	v_lshlrev_b64 v[0:1], 12, v[0:1]
	v_lshl_add_u64 v[0:1], v[4:5], 0, v[0:1]
	global_load_dwordx4 v[0:3], v[0:1], off nt
	v_add_u32_e32 v4, 0x1ce0, v7
	s_waitcnt vmcnt(0)
	ds_write2_b32 v4, v0, v1 offset1:1
	v_add_u32_e32 v0, 0x1ce8, v7
	ds_write2_b32 v0, v2, v3 offset1:1
	v_lshlrev_b32_e32 v0, 3, v12
	v_and_b32_e32 v0, 56, v0
	v_mul_u32_u24_e32 v1, 0x84, v0
	v_lshlrev_b32_e32 v194, 1, v0
	v_lshlrev_b32_e32 v0, 2, v13
	s_waitcnt lgkmcnt(0)
	v_add3_u32 v29, s33, v1, v0
	ds_read2_b32 v[6:7], v29 offset0:33 offset1:41
	ds_read2_b32 v[8:9], v29 offset1:8
	ds_read2_b32 v[10:11], v29 offset0:66 offset1:74
	ds_read2_b32 v[14:15], v29 offset0:99 offset1:107
	ds_read2_b32 v[16:17], v29 offset0:132 offset1:140
	ds_read2_b32 v[18:19], v29 offset0:165 offset1:173
	ds_read2_b32 v[20:21], v29 offset0:198 offset1:206
	ds_read2_b32 v[22:23], v29 offset0:231 offset1:239
	v_lshl_add_u64 v[4:5], s[14:15], 0, v[194:195]
	s_waitcnt lgkmcnt(6)
	v_cvt_pk_bf16_f32 v0, v8, v6
	s_waitcnt lgkmcnt(4)
	v_cvt_pk_bf16_f32 v1, v10, v14
	s_waitcnt lgkmcnt(2)
	v_cvt_pk_bf16_f32 v2, v16, v18
	s_waitcnt lgkmcnt(0)
	v_cvt_pk_bf16_f32 v3, v20, v22
	v_lshl_add_u64 v[24:25], v[4:5], 0, v[24:25]
	v_add_u32_e32 v6, s0, v26
	global_store_dwordx4 v[24:25], v[0:3], off
	v_add_u32_e32 v24, s0, v27
	v_ashrrev_i32_e32 v25, 31, v24
	v_cvt_pk_bf16_f32 v0, v9, v7
	v_ashrrev_i32_e32 v7, 31, v6
	v_lshlrev_b64 v[6:7], 9, v[6:7]
	v_cvt_pk_bf16_f32 v1, v11, v15
	v_cvt_pk_bf16_f32 v2, v17, v19
	v_cvt_pk_bf16_f32 v3, v21, v23
	v_lshl_add_u64 v[6:7], v[4:5], 0, v[6:7]
	global_store_dwordx4 v[6:7], v[0:3], off
	ds_read2_b32 v[6:7], v29 offset0:49 offset1:57
	ds_read2_b32 v[8:9], v29 offset0:16 offset1:24
	ds_read2_b32 v[10:11], v29 offset0:82 offset1:90
	ds_read2_b32 v[14:15], v29 offset0:115 offset1:123
	ds_read2_b32 v[16:17], v29 offset0:148 offset1:156
	ds_read2_b32 v[18:19], v29 offset0:181 offset1:189
	ds_read2_b32 v[20:21], v29 offset0:214 offset1:222
	ds_read2_b32 v[22:23], v29 offset0:247 offset1:255
	v_lshlrev_b64 v[24:25], 9, v[24:25]
	s_waitcnt lgkmcnt(6)
	v_cvt_pk_bf16_f32 v0, v8, v6
	s_waitcnt lgkmcnt(4)
	v_cvt_pk_bf16_f32 v1, v10, v14
	s_waitcnt lgkmcnt(2)
	v_cvt_pk_bf16_f32 v2, v16, v18
	s_waitcnt lgkmcnt(0)
	v_cvt_pk_bf16_f32 v3, v20, v22
	v_lshl_add_u64 v[24:25], v[4:5], 0, v[24:25]
	v_add_u32_e32 v6, s0, v28
	global_store_dwordx4 v[24:25], v[0:3], off
	s_nop 1
	v_cvt_pk_bf16_f32 v0, v9, v7
	v_ashrrev_i32_e32 v7, 31, v6
	v_lshlrev_b64 v[6:7], 9, v[6:7]
	v_cvt_pk_bf16_f32 v1, v11, v15
	v_cvt_pk_bf16_f32 v2, v17, v19
	v_cvt_pk_bf16_f32 v3, v21, v23
	v_lshl_add_u64 v[4:5], v[4:5], 0, v[6:7]
	global_store_dwordx4 v[4:5], v[0:3], off
	s_waitcnt lgkmcnt(0)

.LBB0_825:
	s_andn2_b64 vcc, exec, s[0:1]
	s_cbranch_vccnz .LBB0_843
	s_and_b32 s3, s55, 0xe0
	s_and_b32 s14, s87, 0x7c0
	v_ashrrev_i32_e32 v10, 3, v12
	v_lshlrev_b32_e32 v0, 2, v12
	s_lshl_b32 s0, s3, 2
	v_and_b32_e32 v11, 28, v0
	s_add_u32 s0, s88, s0
	v_add_u32_e32 v8, s14, v10
	s_addc_u32 s1, s89, 0
	v_lshlrev_b32_e32 v194, 2, v11
	v_ashrrev_i32_e32 v9, 31, v8
	v_lshl_add_u64 v[6:7], s[0:1], 0, v[194:195]
	v_lshlrev_b64 v[0:1], 10, v[8:9]
	v_lshl_add_u64 v[0:1], v[6:7], 0, v[0:1]
	global_load_dwordx4 v[0:3], v[0:1], off nt
	v_readlane_b32 s42, v254, 39
	v_readlane_b32 s43, v254, 40
	s_andn2_b64 vcc, exec, s[42:43]
	s_nop 0
	v_cndmask_b32_e64 v4, 0, 1, s[42:43]
	v_cmp_ne_u32_e64 s[0:1], 1, v4
	v_lshl_add_u64 v[4:5], v[8:9], 2, s[8:9]
	s_cbranch_vccnz .LBB0_828
	global_load_dword v14, v[4:5], off
	s_waitcnt vmcnt(0)
	v_pk_mul_f32 v[2:3], v[2:3], v[14:15] op_sel_hi:[1,0]
	v_pk_mul_f32 v[0:1], v[0:1], v[14:15] op_sel_hi:[1,0]
.LBB0_828:
	v_lshl_add_u32 v9, v11, 2, s33
	v_mul_lo_u32 v11, v10, s49
	v_add_u32_e32 v13, v9, v11
	v_add_u32_e32 v9, 8, v10
	s_waitcnt vmcnt(0)
	ds_write2_b32 v13, v0, v1 offset1:1
	ds_write2_b32 v13, v2, v3 offset0:2 offset1:3
	v_add_u32_e32 v0, s14, v9
	v_ashrrev_i32_e32 v1, 31, v0
	v_lshlrev_b64 v[0:1], 10, v[0:1]
	v_lshl_add_u64 v[0:1], v[6:7], 0, v[0:1]
	global_load_dwordx4 v[0:3], v[0:1], off nt
	s_and_b64 vcc, exec, s[0:1]
	s_cbranch_vccnz .LBB0_830
	global_load_dword v14, v[4:5], off offset:32
	s_waitcnt vmcnt(0)
	v_pk_mul_f32 v[2:3], v[2:3], v[14:15] op_sel_hi:[1,0]
	v_pk_mul_f32 v[0:1], v[0:1], v[14:15] op_sel_hi:[1,0]
.LBB0_830:
	v_add_u32_e32 v11, 0x420, v13
	s_waitcnt vmcnt(0)
	ds_write2_b32 v11, v0, v1 offset1:1
	v_add_u32_e32 v0, 0x428, v13
	v_add_u32_e32 v11, 16, v10
	ds_write2_b32 v0, v2, v3 offset1:1
	v_add_u32_e32 v0, s14, v11
	v_ashrrev_i32_e32 v1, 31, v0
	v_lshlrev_b64 v[0:1], 10, v[0:1]
	v_lshl_add_u64 v[0:1], v[6:7], 0, v[0:1]
	global_load_dwordx4 v[0:3], v[0:1], off nt
	s_and_b64 vcc, exec, s[0:1]
	s_cbranch_vccnz .LBB0_832
	global_load_dword v14, v[4:5], off offset:64
	s_waitcnt vmcnt(0)
	v_pk_mul_f32 v[2:3], v[2:3], v[14:15] op_sel_hi:[1,0]
	v_pk_mul_f32 v[0:1], v[0:1], v[14:15] op_sel_hi:[1,0]
.LBB0_832:
	v_add_u32_e32 v14, 0x840, v13
	s_waitcnt vmcnt(0)
	ds_write2_b32 v14, v0, v1 offset1:1
	v_add_u32_e32 v0, 0x848, v13
	v_add_u32_e32 v14, 24, v10
	ds_write2_b32 v0, v2, v3 offset1:1
	v_add_u32_e32 v0, s14, v14
	v_ashrrev_i32_e32 v1, 31, v0
	v_lshlrev_b64 v[0:1], 10, v[0:1]
	v_lshl_add_u64 v[0:1], v[6:7], 0, v[0:1]
	global_load_dwordx4 v[0:3], v[0:1], off nt
	s_and_b64 vcc, exec, s[0:1]
	s_cbranch_vccnz .LBB0_834
	global_load_dword v16, v[4:5], off offset:96
	s_waitcnt vmcnt(0)
	v_pk_mul_f32 v[2:3], v[2:3], v[16:17] op_sel_hi:[1,0]
	v_pk_mul_f32 v[0:1], v[0:1], v[16:17] op_sel_hi:[1,0]
.LBB0_834:
	v_add_u32_e32 v15, 0xc60, v13
	s_waitcnt vmcnt(0)
	ds_write2_b32 v15, v0, v1 offset1:1
	v_add_u32_e32 v0, 0xc68, v13
	ds_write2_b32 v0, v2, v3 offset1:1
	v_add_u32_e32 v0, 32, v8
	v_ashrrev_i32_e32 v1, 31, v0
	v_lshlrev_b64 v[0:1], 10, v[0:1]
	v_lshl_add_u64 v[0:1], v[6:7], 0, v[0:1]
	global_load_dwordx4 v[0:3], v[0:1], off nt
	s_and_b64 vcc, exec, s[0:1]
	s_cbranch_vccnz .LBB0_836
	global_load_dword v16, v[4:5], off offset:128
	s_waitcnt vmcnt(0)
	v_pk_mul_f32 v[2:3], v[2:3], v[16:17] op_sel_hi:[1,0]
	v_pk_mul_f32 v[0:1], v[0:1], v[16:17] op_sel_hi:[1,0]
.LBB0_836:
	v_add_u32_e32 v15, 0x1080, v13
	s_waitcnt vmcnt(0)
	ds_write2_b32 v15, v0, v1 offset1:1
	v_add_u32_e32 v0, 0x1088, v13
	ds_write2_b32 v0, v2, v3 offset1:1
	v_add_u32_e32 v0, 40, v8
	v_ashrrev_i32_e32 v1, 31, v0
	v_lshlrev_b64 v[0:1], 10, v[0:1]
	v_lshl_add_u64 v[0:1], v[6:7], 0, v[0:1]
	global_load_dwordx4 v[0:3], v[0:1], off nt
	s_and_b64 vcc, exec, s[0:1]
	s_cbranch_vccnz .LBB0_838
	global_load_dword v16, v[4:5], off offset:160
	s_waitcnt vmcnt(0)
	v_pk_mul_f32 v[2:3], v[2:3], v[16:17] op_sel_hi:[1,0]
	v_pk_mul_f32 v[0:1], v[0:1], v[16:17] op_sel_hi:[1,0]
.LBB0_838:
	v_add_u32_e32 v15, 0x14a0, v13
	s_waitcnt vmcnt(0)
	ds_write2_b32 v15, v0, v1 offset1:1
	v_add_u32_e32 v0, 0x14a8, v13
	ds_write2_b32 v0, v2, v3 offset1:1
	v_add_u32_e32 v0, 48, v8
	v_ashrrev_i32_e32 v1, 31, v0
	v_lshlrev_b64 v[0:1], 10, v[0:1]
	v_lshl_add_u64 v[0:1], v[6:7], 0, v[0:1]
	global_load_dwordx4 v[0:3], v[0:1], off nt
	s_and_b64 vcc, exec, s[0:1]
	s_cbranch_vccnz .LBB0_840
	global_load_dword v16, v[4:5], off offset:192
	s_waitcnt vmcnt(0)
	v_pk_mul_f32 v[2:3], v[2:3], v[16:17] op_sel_hi:[1,0]
	v_pk_mul_f32 v[0:1], v[0:1], v[16:17] op_sel_hi:[1,0]
.LBB0_840:
	v_add_u32_e32 v15, 0x18c0, v13
	s_waitcnt vmcnt(0)
	ds_write2_b32 v15, v0, v1 offset1:1
	v_add_u32_e32 v0, 0x18c8, v13
	ds_write2_b32 v0, v2, v3 offset1:1
	v_add_u32_e32 v0, 56, v8
	v_ashrrev_i32_e32 v1, 31, v0
	v_lshlrev_b64 v[0:1], 10, v[0:1]
	v_lshl_add_u64 v[0:1], v[6:7], 0, v[0:1]
	global_load_dwordx4 v[0:3], v[0:1], off nt
	s_and_b64 vcc, exec, s[0:1]
	s_cbranch_vccnz .LBB0_842
	global_load_dword v4, v[4:5], off offset:224
	s_waitcnt vmcnt(0)
	v_pk_mul_f32 v[2:3], v[2:3], v[4:5] op_sel_hi:[1,0]
	v_pk_mul_f32 v[0:1], v[0:1], v[4:5] op_sel_hi:[1,0]

.LBB0_844:
	s_andn2_b64 vcc, exec, s[0:1]
	s_cbranch_vccnz .LBB0_846
	s_add_i32 s0, s25, 0x1600
	s_and_b32 s1, s0, 0x1ffc0
	s_and_b32 s0, s55, 0x3e0
	v_ashrrev_i32_e32 v13, 3, v12
	s_lshl_b32 s3, s0, 2
	s_add_u32 s14, s92, s3
	v_lshlrev_b32_e32 v0, 4, v12
	v_add_u32_e32 v6, s1, v13
	s_addc_u32 s15, s96, 0
	v_and_b32_e32 v194, 0x70, v0
	v_ashrrev_i32_e32 v7, 31, v6
	v_lshl_add_u64 v[4:5], s[14:15], 0, v[194:195]
	v_lshlrev_b64 v[0:1], 12, v[6:7]
	v_lshl_add_u64 v[0:1], v[4:5], 0, v[0:1]
	global_load_dwordx4 v[0:3], v[0:1], off nt
	v_mul_lo_u32 v7, v13, s49
	v_add3_u32 v7, s33, v194, v7
	v_add_u32_e32 v26, 8, v13
	v_add_u32_e32 v8, 0x420, v7
	v_add_u32_e32 v27, 16, v13
	v_add_u32_e32 v28, 24, v13
	v_add_u32_e32 v24, s0, v13
	v_ashrrev_i32_e32 v25, 31, v24
	v_lshlrev_b64 v[24:25], 11, v[24:25]
	s_waitcnt vmcnt(0)
	ds_write2_b32 v7, v0, v1 offset1:1
	ds_write2_b32 v7, v2, v3 offset0:2 offset1:3
	v_add_u32_e32 v0, s1, v26
	v_ashrrev_i32_e32 v1, 31, v0
	v_lshlrev_b64 v[0:1], 12, v[0:1]
	v_lshl_add_u64 v[0:1], v[4:5], 0, v[0:1]
	global_load_dwordx4 v[0:3], v[0:1], off nt
	s_waitcnt vmcnt(0)
	ds_write2_b32 v8, v0, v1 offset1:1
	v_add_u32_e32 v0, 0x428, v7
	ds_write2_b32 v0, v2, v3 offset1:1
	v_add_u32_e32 v0, s1, v27
	v_ashrrev_i32_e32 v1, 31, v0
	v_lshlrev_b64 v[0:1], 12, v[0:1]
	v_lshl_add_u64 v[0:1], v[4:5], 0, v[0:1]
	global_load_dwordx4 v[0:3], v[0:1], off nt
	v_add_u32_e32 v8, 0x840, v7
	s_waitcnt vmcnt(0)
	ds_write2_b32 v8, v0, v1 offset1:1
	v_add_u32_e32 v0, 0x848, v7
	ds_write2_b32 v0, v2, v3 offset1:1
	v_add_u32_e32 v0, s1, v28
	v_ashrrev_i32_e32 v1, 31, v0
	v_lshlrev_b64 v[0:1], 12, v[0:1]
	v_lshl_add_u64 v[0:1], v[4:5], 0, v[0:1]
	global_load_dwordx4 v[0:3], v[0:1], off nt
	v_add_u32_e32 v8, 0xc60, v7
	s_lshl_b32 s1, s1, 1
	s_add_u32 s14, s30, s1
	s_addc_u32 s15, s31, 0
	s_waitcnt vmcnt(0)
	ds_write2_b32 v8, v0, v1 offset1:1
	v_add_u32_e32 v0, 0xc68, v7
	ds_write2_b32 v0, v2, v3 offset1:1
	v_add_u32_e32 v0, 32, v6
	v_ashrrev_i32_e32 v1, 31, v0
	v_lshlrev_b64 v[0:1], 12, v[0:1]
	v_lshl_add_u64 v[0:1], v[4:5], 0, v[0:1]
	global_load_dwordx4 v[0:3], v[0:1], off nt
	v_add_u32_e32 v8, 0x1080, v7
	s_waitcnt vmcnt(0)
	ds_write2_b32 v8, v0, v1 offset1:1
	v_add_u32_e32 v0, 0x1088, v7
	ds_write2_b32 v0, v2, v3 offset1:1
	v_add_u32_e32 v0, 40, v6
	v_ashrrev_i32_e32 v1, 31, v0
	v_lshlrev_b64 v[0:1], 12, v[0:1]
	v_lshl_add_u64 v[0:1], v[4:5], 0, v[0:1]
	global_load_dwordx4 v[0:3], v[0:1], off nt
	v_add_u32_e32 v8, 0x14a0, v7
	s_waitcnt vmcnt(0)
	ds_write2_b32 v8, v0, v1 offset1:1
	v_add_u32_e32 v0, 0x14a8, v7
	ds_write2_b32 v0, v2, v3 offset1:1
	v_add_u32_e32 v0, 48, v6
	v_ashrrev_i32_e32 v1, 31, v0
	v_lshlrev_b64 v[0:1], 12, v[0:1]
	v_lshl_add_u64 v[0:1], v[4:5], 0, v[0:1]
	global_load_dwordx4 v[0:3], v[0:1], off nt
	v_add_u32_e32 v8, 0x18c0, v7
	s_waitcnt vmcnt(0)
	ds_write2_b32 v8, v0, v1 offset1:1
	v_add_u32_e32 v0, 0x18c8, v7
	ds_write2_b32 v0, v2, v3 offset1:1
	v_add_u32_e32 v0, 56, v6
	v_ashrrev_i32_e32 v1, 31, v0
	v_lshlrev_b64 v[0:1], 12, v[0:1]
	v_lshl_add_u64 v[0:1], v[4:5], 0, v[0:1]
	global_load_dwordx4 v[0:3], v[0:1], off nt
	v_add_u32_e32 v4, 0x1ce0, v7
	s_waitcnt vmcnt(0)
	ds_write2_b32 v4, v0, v1 offset1:1
	v_add_u32_e32 v0, 0x1ce8, v7
	ds_write2_b32 v0, v2, v3 offset1:1
	v_lshlrev_b32_e32 v0, 3, v12
	v_and_b32_e32 v0, 56, v0
	v_mul_u32_u24_e32 v1, 0x84, v0
	v_lshlrev_b32_e32 v194, 1, v0
	v_lshlrev_b32_e32 v0, 2, v13
	s_waitcnt lgkmcnt(0)
	v_add3_u32 v29, s33, v1, v0
	ds_read2_b32 v[6:7], v29 offset0:33 offset1:41
	ds_read2_b32 v[8:9], v29 offset1:8
	ds_read2_b32 v[10:11], v29 offset0:66 offset1:74
	ds_read2_b32 v[14:15], v29 offset0:99 offset1:107
	ds_read2_b32 v[16:17], v29 offset0:132 offset1:140
	ds_read2_b32 v[18:19], v29 offset0:165 offset1:173
	ds_read2_b32 v[20:21], v29 offset0:198 offset1:206
	ds_read2_b32 v[22:23], v29 offset0:231 offset1:239
	v_lshl_add_u64 v[4:5], s[14:15], 0, v[194:195]
	s_waitcnt lgkmcnt(6)
	v_cvt_pk_bf16_f32 v0, v8, v6
	s_waitcnt lgkmcnt(4)
	v_cvt_pk_bf16_f32 v1, v10, v14
	s_waitcnt lgkmcnt(2)
	v_cvt_pk_bf16_f32 v2, v16, v18
	s_waitcnt lgkmcnt(0)
	v_cvt_pk_bf16_f32 v3, v20, v22
	v_lshl_add_u64 v[24:25], v[4:5], 0, v[24:25]
	v_add_u32_e32 v6, s0, v26
	global_store_dwordx4 v[24:25], v[0:3], off
	v_add_u32_e32 v24, s0, v27
	v_ashrrev_i32_e32 v25, 31, v24
	v_cvt_pk_bf16_f32 v0, v9, v7
	v_ashrrev_i32_e32 v7, 31, v6
	v_lshlrev_b64 v[6:7], 11, v[6:7]
	v_cvt_pk_bf16_f32 v1, v11, v15
	v_cvt_pk_bf16_f32 v2, v17, v19
	v_cvt_pk_bf16_f32 v3, v21, v23
	v_lshl_add_u64 v[6:7], v[4:5], 0, v[6:7]
	global_store_dwordx4 v[6:7], v[0:3], off
	ds_read2_b32 v[6:7], v29 offset0:49 offset1:57
	ds_read2_b32 v[8:9], v29 offset0:16 offset1:24
	ds_read2_b32 v[10:11], v29 offset0:82 offset1:90
	ds_read2_b32 v[14:15], v29 offset0:115 offset1:123
	ds_read2_b32 v[16:17], v29 offset0:148 offset1:156
	ds_read2_b32 v[18:19], v29 offset0:181 offset1:189
	ds_read2_b32 v[20:21], v29 offset0:214 offset1:222
	ds_read2_b32 v[22:23], v29 offset0:247 offset1:255
	v_lshlrev_b64 v[24:25], 11, v[24:25]
	s_waitcnt lgkmcnt(6)
	v_cvt_pk_bf16_f32 v0, v8, v6
	s_waitcnt lgkmcnt(4)
	v_cvt_pk_bf16_f32 v1, v10, v14
	s_waitcnt lgkmcnt(2)
	v_cvt_pk_bf16_f32 v2, v16, v18
	s_waitcnt lgkmcnt(0)
	v_cvt_pk_bf16_f32 v3, v20, v22
	v_lshl_add_u64 v[24:25], v[4:5], 0, v[24:25]
	v_add_u32_e32 v6, s0, v28
	global_store_dwordx4 v[24:25], v[0:3], off
	s_nop 1
	v_cvt_pk_bf16_f32 v0, v9, v7
	v_ashrrev_i32_e32 v7, 31, v6
	v_lshlrev_b64 v[6:7], 11, v[6:7]
	v_cvt_pk_bf16_f32 v1, v11, v15
	v_cvt_pk_bf16_f32 v2, v17, v19
	v_cvt_pk_bf16_f32 v3, v21, v23
	v_lshl_add_u64 v[4:5], v[4:5], 0, v[6:7]
	global_store_dwordx4 v[4:5], v[0:3], off
	s_waitcnt lgkmcnt(0)

.LBB0_847:
	s_andn2_b64 vcc, exec, s[0:1]
	s_cbranch_vccnz .LBB0_849
	s_add_i32 s0, s25, 0x1a00
	s_and_b32 s1, s0, 0x1ffc0
	s_and_b32 s0, s55, 0x3e0
	v_ashrrev_i32_e32 v13, 3, v12
	s_lshl_b32 s3, s0, 2
	s_add_u32 s14, s97, s3
	v_lshlrev_b32_e32 v0, 4, v12
	v_add_u32_e32 v6, s1, v13
	s_addc_u32 s15, s18, 0
	v_and_b32_e32 v194, 0x70, v0
	v_ashrrev_i32_e32 v7, 31, v6
	v_lshl_add_u64 v[4:5], s[14:15], 0, v[194:195]
	v_lshlrev_b64 v[0:1], 12, v[6:7]
	v_lshl_add_u64 v[0:1], v[4:5], 0, v[0:1]
	global_load_dwordx4 v[0:3], v[0:1], off nt
	v_mul_lo_u32 v7, v13, s49
	v_add3_u32 v7, s33, v194, v7
	v_add_u32_e32 v26, 8, v13
	v_add_u32_e32 v8, 0x420, v7
	v_add_u32_e32 v27, 16, v13
	v_add_u32_e32 v28, 24, v13
	v_add_u32_e32 v24, s0, v13
	v_ashrrev_i32_e32 v25, 31, v24
	v_lshlrev_b64 v[24:25], 11, v[24:25]
	s_waitcnt vmcnt(0)
	ds_write2_b32 v7, v0, v1 offset1:1
	ds_write2_b32 v7, v2, v3 offset0:2 offset1:3
	v_add_u32_e32 v0, s1, v26
	v_ashrrev_i32_e32 v1, 31, v0
	v_lshlrev_b64 v[0:1], 12, v[0:1]
	v_lshl_add_u64 v[0:1], v[4:5], 0, v[0:1]
	global_load_dwordx4 v[0:3], v[0:1], off nt
	s_waitcnt vmcnt(0)
	ds_write2_b32 v8, v0, v1 offset1:1
	v_add_u32_e32 v0, 0x428, v7
	ds_write2_b32 v0, v2, v3 offset1:1
	v_add_u32_e32 v0, s1, v27
	v_ashrrev_i32_e32 v1, 31, v0
	v_lshlrev_b64 v[0:1], 12, v[0:1]
	v_lshl_add_u64 v[0:1], v[4:5], 0, v[0:1]
	global_load_dwordx4 v[0:3], v[0:1], off nt
	v_add_u32_e32 v8, 0x840, v7
	s_waitcnt vmcnt(0)
	ds_write2_b32 v8, v0, v1 offset1:1
	v_add_u32_e32 v0, 0x848, v7
	ds_write2_b32 v0, v2, v3 offset1:1
	v_add_u32_e32 v0, s1, v28
	v_ashrrev_i32_e32 v1, 31, v0
	v_lshlrev_b64 v[0:1], 12, v[0:1]
	v_lshl_add_u64 v[0:1], v[4:5], 0, v[0:1]
	global_load_dwordx4 v[0:3], v[0:1], off nt
	v_add_u32_e32 v8, 0xc60, v7
	s_lshl_b32 s1, s1, 1
	s_add_u32 s14, s16, s1
	s_addc_u32 s15, s20, 0
	s_waitcnt vmcnt(0)
	ds_write2_b32 v8, v0, v1 offset1:1
	v_add_u32_e32 v0, 0xc68, v7
	ds_write2_b32 v0, v2, v3 offset1:1
	v_add_u32_e32 v0, 32, v6
	v_ashrrev_i32_e32 v1, 31, v0
	v_lshlrev_b64 v[0:1], 12, v[0:1]
	v_lshl_add_u64 v[0:1], v[4:5], 0, v[0:1]
	global_load_dwordx4 v[0:3], v[0:1], off nt
	v_add_u32_e32 v8, 0x1080, v7
	s_waitcnt vmcnt(0)
	ds_write2_b32 v8, v0, v1 offset1:1
	v_add_u32_e32 v0, 0x1088, v7
	ds_write2_b32 v0, v2, v3 offset1:1
	v_add_u32_e32 v0, 40, v6
	v_ashrrev_i32_e32 v1, 31, v0
	v_lshlrev_b64 v[0:1], 12, v[0:1]
	v_lshl_add_u64 v[0:1], v[4:5], 0, v[0:1]
	global_load_dwordx4 v[0:3], v[0:1], off nt
	v_add_u32_e32 v8, 0x14a0, v7
	s_waitcnt vmcnt(0)
	ds_write2_b32 v8, v0, v1 offset1:1
	v_add_u32_e32 v0, 0x14a8, v7
	ds_write2_b32 v0, v2, v3 offset1:1
	v_add_u32_e32 v0, 48, v6
	v_ashrrev_i32_e32 v1, 31, v0
	v_lshlrev_b64 v[0:1], 12, v[0:1]
	v_lshl_add_u64 v[0:1], v[4:5], 0, v[0:1]
	global_load_dwordx4 v[0:3], v[0:1], off nt
	v_add_u32_e32 v8, 0x18c0, v7
	s_waitcnt vmcnt(0)
	ds_write2_b32 v8, v0, v1 offset1:1
	v_add_u32_e32 v0, 0x18c8, v7
	ds_write2_b32 v0, v2, v3 offset1:1
	v_add_u32_e32 v0, 56, v6
	v_ashrrev_i32_e32 v1, 31, v0
	v_lshlrev_b64 v[0:1], 12, v[0:1]
	v_lshl_add_u64 v[0:1], v[4:5], 0, v[0:1]
	global_load_dwordx4 v[0:3], v[0:1], off nt
	v_add_u32_e32 v4, 0x1ce0, v7
	s_waitcnt vmcnt(0)
	ds_write2_b32 v4, v0, v1 offset1:1
	v_add_u32_e32 v0, 0x1ce8, v7
	ds_write2_b32 v0, v2, v3 offset1:1
	v_lshlrev_b32_e32 v0, 3, v12
	v_and_b32_e32 v0, 56, v0
	v_mul_u32_u24_e32 v1, 0x84, v0
	v_lshlrev_b32_e32 v194, 1, v0
	v_lshlrev_b32_e32 v0, 2, v13
	s_waitcnt lgkmcnt(0)
	v_add3_u32 v29, s33, v1, v0
	ds_read2_b32 v[6:7], v29 offset0:33 offset1:41
	ds_read2_b32 v[8:9], v29 offset1:8
	ds_read2_b32 v[10:11], v29 offset0:66 offset1:74
	ds_read2_b32 v[14:15], v29 offset0:99 offset1:107
	ds_read2_b32 v[16:17], v29 offset0:132 offset1:140
	ds_read2_b32 v[18:19], v29 offset0:165 offset1:173
	ds_read2_b32 v[20:21], v29 offset0:198 offset1:206
	ds_read2_b32 v[22:23], v29 offset0:231 offset1:239
	v_lshl_add_u64 v[4:5], s[14:15], 0, v[194:195]
	s_waitcnt lgkmcnt(6)
	v_cvt_pk_bf16_f32 v0, v8, v6
	s_waitcnt lgkmcnt(4)
	v_cvt_pk_bf16_f32 v1, v10, v14
	s_waitcnt lgkmcnt(2)
	v_cvt_pk_bf16_f32 v2, v16, v18
	s_waitcnt lgkmcnt(0)
	v_cvt_pk_bf16_f32 v3, v20, v22
	v_lshl_add_u64 v[24:25], v[4:5], 0, v[24:25]
	v_add_u32_e32 v6, s0, v26
	global_store_dwordx4 v[24:25], v[0:3], off
	v_add_u32_e32 v24, s0, v27
	v_ashrrev_i32_e32 v25, 31, v24
	v_cvt_pk_bf16_f32 v0, v9, v7
	v_ashrrev_i32_e32 v7, 31, v6
	v_lshlrev_b64 v[6:7], 11, v[6:7]
	v_cvt_pk_bf16_f32 v1, v11, v15
	v_cvt_pk_bf16_f32 v2, v17, v19
	v_cvt_pk_bf16_f32 v3, v21, v23
	v_lshl_add_u64 v[6:7], v[4:5], 0, v[6:7]
	global_store_dwordx4 v[6:7], v[0:3], off
	ds_read2_b32 v[6:7], v29 offset0:49 offset1:57
	ds_read2_b32 v[8:9], v29 offset0:16 offset1:24
	ds_read2_b32 v[10:11], v29 offset0:82 offset1:90
	ds_read2_b32 v[14:15], v29 offset0:115 offset1:123
	ds_read2_b32 v[16:17], v29 offset0:148 offset1:156
	ds_read2_b32 v[18:19], v29 offset0:181 offset1:189
	ds_read2_b32 v[20:21], v29 offset0:214 offset1:222
	ds_read2_b32 v[22:23], v29 offset0:247 offset1:255
	v_lshlrev_b64 v[24:25], 11, v[24:25]
	s_waitcnt lgkmcnt(6)
	v_cvt_pk_bf16_f32 v0, v8, v6
	s_waitcnt lgkmcnt(4)
	v_cvt_pk_bf16_f32 v1, v10, v14
	s_waitcnt lgkmcnt(2)
	v_cvt_pk_bf16_f32 v2, v16, v18
	s_waitcnt lgkmcnt(0)
	v_cvt_pk_bf16_f32 v3, v20, v22
	v_lshl_add_u64 v[24:25], v[4:5], 0, v[24:25]
	v_add_u32_e32 v6, s0, v28
	global_store_dwordx4 v[24:25], v[0:3], off
	s_nop 1
	v_cvt_pk_bf16_f32 v0, v9, v7
	v_ashrrev_i32_e32 v7, 31, v6
	v_lshlrev_b64 v[6:7], 11, v[6:7]
	v_cvt_pk_bf16_f32 v1, v11, v15
	v_cvt_pk_bf16_f32 v2, v17, v19
	v_cvt_pk_bf16_f32 v3, v21, v23
	v_lshl_add_u64 v[4:5], v[4:5], 0, v[6:7]
	global_store_dwordx4 v[4:5], v[0:3], off
	s_waitcnt lgkmcnt(0)

.LBB0_850:
	s_andn2_b64 vcc, exec, s[0:1]
	s_cbranch_vccnz .LBB0_852
	s_add_i32 s0, s25, 0x1e00
	s_and_b32 s1, s0, 0x1ffc0
	s_and_b32 s0, s55, 0x3e0
	v_ashrrev_i32_e32 v13, 3, v12
	s_lshl_b32 s3, s0, 2
	s_add_u32 s14, s19, s3
	v_lshlrev_b32_e32 v0, 4, v12
	v_add_u32_e32 v6, s1, v13
	s_addc_u32 s15, s22, 0
	v_and_b32_e32 v194, 0x70, v0
	v_ashrrev_i32_e32 v7, 31, v6
	v_lshl_add_u64 v[4:5], s[14:15], 0, v[194:195]
	v_lshlrev_b64 v[0:1], 12, v[6:7]
	v_lshl_add_u64 v[0:1], v[4:5], 0, v[0:1]
	global_load_dwordx4 v[0:3], v[0:1], off nt
	v_mul_lo_u32 v7, v13, s49
	v_add3_u32 v7, s33, v194, v7
	v_add_u32_e32 v26, 8, v13
	v_add_u32_e32 v8, 0x420, v7
	v_add_u32_e32 v27, 16, v13
	v_add_u32_e32 v28, 24, v13
	v_add_u32_e32 v24, s0, v13
	v_ashrrev_i32_e32 v25, 31, v24
	v_lshlrev_b64 v[24:25], 11, v[24:25]
	s_waitcnt vmcnt(0)
	ds_write2_b32 v7, v0, v1 offset1:1
	ds_write2_b32 v7, v2, v3 offset0:2 offset1:3
	v_add_u32_e32 v0, s1, v26
	v_ashrrev_i32_e32 v1, 31, v0
	v_lshlrev_b64 v[0:1], 12, v[0:1]
	v_lshl_add_u64 v[0:1], v[4:5], 0, v[0:1]
	global_load_dwordx4 v[0:3], v[0:1], off nt
	s_waitcnt vmcnt(0)
	ds_write2_b32 v8, v0, v1 offset1:1
	v_add_u32_e32 v0, 0x428, v7
	ds_write2_b32 v0, v2, v3 offset1:1
	v_add_u32_e32 v0, s1, v27
	v_ashrrev_i32_e32 v1, 31, v0
	v_lshlrev_b64 v[0:1], 12, v[0:1]
	v_lshl_add_u64 v[0:1], v[4:5], 0, v[0:1]
	global_load_dwordx4 v[0:3], v[0:1], off nt
	v_add_u32_e32 v8, 0x840, v7
	s_waitcnt vmcnt(0)
	ds_write2_b32 v8, v0, v1 offset1:1
	v_add_u32_e32 v0, 0x848, v7
	ds_write2_b32 v0, v2, v3 offset1:1
	v_add_u32_e32 v0, s1, v28
	v_ashrrev_i32_e32 v1, 31, v0
	v_lshlrev_b64 v[0:1], 12, v[0:1]
	v_lshl_add_u64 v[0:1], v[4:5], 0, v[0:1]
	global_load_dwordx4 v[0:3], v[0:1], off nt
	v_add_u32_e32 v8, 0xc60, v7
	s_lshl_b32 s1, s1, 1
	s_add_u32 s14, s35, s1
	s_addc_u32 s15, s26, 0
	s_waitcnt vmcnt(0)
	ds_write2_b32 v8, v0, v1 offset1:1
	v_add_u32_e32 v0, 0xc68, v7
	ds_write2_b32 v0, v2, v3 offset1:1
	v_add_u32_e32 v0, 32, v6
	v_ashrrev_i32_e32 v1, 31, v0
	v_lshlrev_b64 v[0:1], 12, v[0:1]
	v_lshl_add_u64 v[0:1], v[4:5], 0, v[0:1]
	global_load_dwordx4 v[0:3], v[0:1], off nt
	v_add_u32_e32 v8, 0x1080, v7
	s_waitcnt vmcnt(0)
	ds_write2_b32 v8, v0, v1 offset1:1
	v_add_u32_e32 v0, 0x1088, v7
	ds_write2_b32 v0, v2, v3 offset1:1
	v_add_u32_e32 v0, 40, v6
	v_ashrrev_i32_e32 v1, 31, v0
	v_lshlrev_b64 v[0:1], 12, v[0:1]
	v_lshl_add_u64 v[0:1], v[4:5], 0, v[0:1]
	global_load_dwordx4 v[0:3], v[0:1], off nt
	v_add_u32_e32 v8, 0x14a0, v7
	s_waitcnt vmcnt(0)
	ds_write2_b32 v8, v0, v1 offset1:1
	v_add_u32_e32 v0, 0x14a8, v7
	ds_write2_b32 v0, v2, v3 offset1:1
	v_add_u32_e32 v0, 48, v6
	v_ashrrev_i32_e32 v1, 31, v0
	v_lshlrev_b64 v[0:1], 12, v[0:1]
	v_lshl_add_u64 v[0:1], v[4:5], 0, v[0:1]
	global_load_dwordx4 v[0:3], v[0:1], off nt
	v_add_u32_e32 v8, 0x18c0, v7
	s_waitcnt vmcnt(0)
	ds_write2_b32 v8, v0, v1 offset1:1
	v_add_u32_e32 v0, 0x18c8, v7
	ds_write2_b32 v0, v2, v3 offset1:1
	v_add_u32_e32 v0, 56, v6
	v_ashrrev_i32_e32 v1, 31, v0
	v_lshlrev_b64 v[0:1], 12, v[0:1]
	v_lshl_add_u64 v[0:1], v[4:5], 0, v[0:1]
	global_load_dwordx4 v[0:3], v[0:1], off nt
	v_add_u32_e32 v4, 0x1ce0, v7
	s_waitcnt vmcnt(0)
	ds_write2_b32 v4, v0, v1 offset1:1
	v_add_u32_e32 v0, 0x1ce8, v7
	ds_write2_b32 v0, v2, v3 offset1:1
	v_lshlrev_b32_e32 v0, 3, v12
	v_and_b32_e32 v0, 56, v0
	v_mul_u32_u24_e32 v1, 0x84, v0
	v_lshlrev_b32_e32 v194, 1, v0
	v_lshlrev_b32_e32 v0, 2, v13
	s_waitcnt lgkmcnt(0)
	v_add3_u32 v29, s33, v1, v0
	ds_read2_b32 v[6:7], v29 offset0:33 offset1:41
	ds_read2_b32 v[8:9], v29 offset1:8
	ds_read2_b32 v[10:11], v29 offset0:66 offset1:74
	ds_read2_b32 v[14:15], v29 offset0:99 offset1:107
	ds_read2_b32 v[16:17], v29 offset0:132 offset1:140
	ds_read2_b32 v[18:19], v29 offset0:165 offset1:173
	ds_read2_b32 v[20:21], v29 offset0:198 offset1:206
	ds_read2_b32 v[22:23], v29 offset0:231 offset1:239
	v_lshl_add_u64 v[4:5], s[14:15], 0, v[194:195]
	s_waitcnt lgkmcnt(6)
	v_cvt_pk_bf16_f32 v0, v8, v6
	s_waitcnt lgkmcnt(4)
	v_cvt_pk_bf16_f32 v1, v10, v14
	s_waitcnt lgkmcnt(2)
	v_cvt_pk_bf16_f32 v2, v16, v18
	s_waitcnt lgkmcnt(0)
	v_cvt_pk_bf16_f32 v3, v20, v22
	v_lshl_add_u64 v[24:25], v[4:5], 0, v[24:25]
	v_add_u32_e32 v6, s0, v26
	global_store_dwordx4 v[24:25], v[0:3], off
	v_add_u32_e32 v24, s0, v27
	v_ashrrev_i32_e32 v25, 31, v24
	v_cvt_pk_bf16_f32 v0, v9, v7
	v_ashrrev_i32_e32 v7, 31, v6
	v_lshlrev_b64 v[6:7], 11, v[6:7]
	v_cvt_pk_bf16_f32 v1, v11, v15
	v_cvt_pk_bf16_f32 v2, v17, v19
	v_cvt_pk_bf16_f32 v3, v21, v23
	v_lshl_add_u64 v[6:7], v[4:5], 0, v[6:7]
	global_store_dwordx4 v[6:7], v[0:3], off
	ds_read2_b32 v[6:7], v29 offset0:49 offset1:57
	ds_read2_b32 v[8:9], v29 offset0:16 offset1:24
	ds_read2_b32 v[10:11], v29 offset0:82 offset1:90
	ds_read2_b32 v[14:15], v29 offset0:115 offset1:123
	ds_read2_b32 v[16:17], v29 offset0:148 offset1:156
	ds_read2_b32 v[18:19], v29 offset0:181 offset1:189
	ds_read2_b32 v[20:21], v29 offset0:214 offset1:222
	ds_read2_b32 v[22:23], v29 offset0:247 offset1:255
	v_lshlrev_b64 v[24:25], 11, v[24:25]
	s_waitcnt lgkmcnt(6)
	v_cvt_pk_bf16_f32 v0, v8, v6
	s_waitcnt lgkmcnt(4)
	v_cvt_pk_bf16_f32 v1, v10, v14
	s_waitcnt lgkmcnt(2)
	v_cvt_pk_bf16_f32 v2, v16, v18
	s_waitcnt lgkmcnt(0)
	v_cvt_pk_bf16_f32 v3, v20, v22
	v_lshl_add_u64 v[24:25], v[4:5], 0, v[24:25]
	v_add_u32_e32 v6, s0, v28
	global_store_dwordx4 v[24:25], v[0:3], off
	s_nop 1
	v_cvt_pk_bf16_f32 v0, v9, v7
	v_ashrrev_i32_e32 v7, 31, v6
	v_lshlrev_b64 v[6:7], 11, v[6:7]
	v_cvt_pk_bf16_f32 v1, v11, v15
	v_cvt_pk_bf16_f32 v2, v17, v19
	v_cvt_pk_bf16_f32 v3, v21, v23
	v_lshl_add_u64 v[4:5], v[4:5], 0, v[6:7]
	global_store_dwordx4 v[4:5], v[0:3], off
	s_waitcnt lgkmcnt(0)

.LBB0_864:
	s_lshl_b32 s14, s1, 6
	s_ashr_i32 s1, s0, 31
	v_lshlrev_b32_e32 v0, 2, v12
	s_lshl_b64 s[0:1], s[0:1], 2
	v_and_b32_e32 v11, 28, v0
	s_add_u32 s0, s23, s0
	v_ashrrev_i32_e32 v10, 3, v12
	s_addc_u32 s1, s54, s1
	v_lshlrev_b32_e32 v194, 2, v11
	v_lshl_add_u64 v[6:7], s[0:1], 0, v[194:195]
	v_add_u32_e32 v8, s14, v10
	v_mad_i64_i32 v[0:1], s[0:1], v8, s52, v[6:7]
	global_load_dwordx4 v[0:3], v[0:1], off nt
	v_ashrrev_i32_e32 v9, 31, v8
	v_cndmask_b32_e64 v4, 0, 1, s[50:51]
	v_cmp_ne_u32_e64 s[0:1], 1, v4
	s_andn2_b64 vcc, exec, s[50:51]
	v_lshl_add_u64 v[4:5], v[8:9], 2, s[10:11]
	s_cbranch_vccnz .LBB0_866
	global_load_dword v14, v[4:5], off
	s_waitcnt vmcnt(0)
	v_pk_mul_f32 v[2:3], v[2:3], v[14:15] op_sel_hi:[1,0]
	v_pk_mul_f32 v[0:1], v[0:1], v[14:15] op_sel_hi:[1,0]
.LBB0_866:
	v_lshl_add_u32 v9, v11, 2, s33
	v_mul_lo_u32 v11, v10, s49
	v_add_u32_e32 v14, v9, v11
	v_add_u32_e32 v9, 8, v10
	s_waitcnt vmcnt(0)
	ds_write2_b32 v14, v0, v1 offset1:1
	ds_write2_b32 v14, v2, v3 offset0:2 offset1:3
	v_add_u32_e32 v0, s14, v9
	v_mad_i64_i32 v[0:1], s[42:43], v0, s52, v[6:7]
	global_load_dwordx4 v[0:3], v[0:1], off nt
	s_and_b64 vcc, exec, s[0:1]
	s_cbranch_vccnz .LBB0_868
	global_load_dword v16, v[4:5], off offset:32
	s_waitcnt vmcnt(0)
	v_pk_mul_f32 v[2:3], v[2:3], v[16:17] op_sel_hi:[1,0]
	v_pk_mul_f32 v[0:1], v[0:1], v[16:17] op_sel_hi:[1,0]
.LBB0_868:
	v_add_u32_e32 v11, 0x420, v14
	s_waitcnt vmcnt(0)
	ds_write2_b32 v11, v0, v1 offset1:1
	v_add_u32_e32 v0, 0x428, v14
	v_add_u32_e32 v11, 16, v10
	ds_write2_b32 v0, v2, v3 offset1:1
	v_add_u32_e32 v0, s14, v11
	v_mad_i64_i32 v[0:1], s[42:43], v0, s52, v[6:7]
	global_load_dwordx4 v[0:3], v[0:1], off nt
	s_and_b64 vcc, exec, s[0:1]
	s_cbranch_vccnz .LBB0_870
	global_load_dword v16, v[4:5], off offset:64
	s_waitcnt vmcnt(0)
	v_pk_mul_f32 v[2:3], v[2:3], v[16:17] op_sel_hi:[1,0]
	v_pk_mul_f32 v[0:1], v[0:1], v[16:17] op_sel_hi:[1,0]
.LBB0_870:
	v_add_u32_e32 v13, 0x840, v14
	s_waitcnt vmcnt(0)
	ds_write2_b32 v13, v0, v1 offset1:1
	v_add_u32_e32 v0, 0x848, v14
	v_add_u32_e32 v13, 24, v10
	ds_write2_b32 v0, v2, v3 offset1:1
	v_add_u32_e32 v0, s14, v13
	v_mad_i64_i32 v[0:1], s[42:43], v0, s52, v[6:7]
	global_load_dwordx4 v[0:3], v[0:1], off nt
	s_and_b64 vcc, exec, s[0:1]
	s_cbranch_vccnz .LBB0_872
	global_load_dword v16, v[4:5], off offset:96
	s_waitcnt vmcnt(0)
	v_pk_mul_f32 v[2:3], v[2:3], v[16:17] op_sel_hi:[1,0]
	v_pk_mul_f32 v[0:1], v[0:1], v[16:17] op_sel_hi:[1,0]
.LBB0_872:
	v_add_u32_e32 v15, 0xc60, v14
	s_waitcnt vmcnt(0)
	ds_write2_b32 v15, v0, v1 offset1:1
	v_add_u32_e32 v0, 0xc68, v14
	ds_write2_b32 v0, v2, v3 offset1:1
	v_add_u32_e32 v0, 32, v8
	v_mad_i64_i32 v[0:1], s[42:43], v0, s52, v[6:7]
	global_load_dwordx4 v[0:3], v[0:1], off nt
	s_and_b64 vcc, exec, s[0:1]
	s_cbranch_vccnz .LBB0_874
	global_load_dword v16, v[4:5], off offset:128
	s_waitcnt vmcnt(0)
	v_pk_mul_f32 v[2:3], v[2:3], v[16:17] op_sel_hi:[1,0]
	v_pk_mul_f32 v[0:1], v[0:1], v[16:17] op_sel_hi:[1,0]
.LBB0_874:
	v_add_u32_e32 v15, 0x1080, v14
	s_waitcnt vmcnt(0)
	ds_write2_b32 v15, v0, v1 offset1:1
	v_add_u32_e32 v0, 0x1088, v14
	ds_write2_b32 v0, v2, v3 offset1:1
	v_add_u32_e32 v0, 40, v8
	v_mad_i64_i32 v[0:1], s[42:43], v0, s52, v[6:7]
	global_load_dwordx4 v[0:3], v[0:1], off nt
	s_and_b64 vcc, exec, s[0:1]
	s_cbranch_vccnz .LBB0_876
	global_load_dword v16, v[4:5], off offset:160
	s_waitcnt vmcnt(0)
	v_pk_mul_f32 v[2:3], v[2:3], v[16:17] op_sel_hi:[1,0]
	v_pk_mul_f32 v[0:1], v[0:1], v[16:17] op_sel_hi:[1,0]
.LBB0_876:
	v_add_u32_e32 v15, 0x14a0, v14
	s_waitcnt vmcnt(0)
	ds_write2_b32 v15, v0, v1 offset1:1
	v_add_u32_e32 v0, 0x14a8, v14
	ds_write2_b32 v0, v2, v3 offset1:1
	v_add_u32_e32 v0, 48, v8
	v_mad_i64_i32 v[0:1], s[42:43], v0, s52, v[6:7]
	global_load_dwordx4 v[0:3], v[0:1], off nt
	s_and_b64 vcc, exec, s[0:1]
	s_cbranch_vccnz .LBB0_878
	global_load_dword v16, v[4:5], off offset:192
	s_waitcnt vmcnt(0)
	v_pk_mul_f32 v[2:3], v[2:3], v[16:17] op_sel_hi:[1,0]
	v_pk_mul_f32 v[0:1], v[0:1], v[16:17] op_sel_hi:[1,0]
.LBB0_878:
	v_add_u32_e32 v15, 0x18c0, v14
	s_waitcnt vmcnt(0)
	ds_write2_b32 v15, v0, v1 offset1:1
	v_add_u32_e32 v0, 0x18c8, v14
	ds_write2_b32 v0, v2, v3 offset1:1
	v_add_u32_e32 v0, 56, v8
	v_mad_i64_i32 v[0:1], s[42:43], v0, s52, v[6:7]
	global_load_dwordx4 v[0:3], v[0:1], off nt
	s_and_b64 vcc, exec, s[0:1]
	s_cbranch_vccnz .LBB0_793
	global_load_dword v4, v[4:5], off offset:224
	s_waitcnt vmcnt(0)
	v_pk_mul_f32 v[2:3], v[2:3], v[4:5] op_sel_hi:[1,0]
	v_pk_mul_f32 v[0:1], v[0:1], v[4:5] op_sel_hi:[1,0]
	s_branch .LBB0_793
